# scan waves: LDS reads issued four steps ahead, one lgkmcnt wait per two steps
# baseline (speedup 1.0000x reference)
.Lsc_S_go:
	ds_read_b128 v[44:47], v34 offset:32768
	ds_read_b128 v[156:159], v35 offset:0
	ds_read_b128 v[76:79], v34 offset:0
	ds_read_b128 v[80:83], v34 offset:256
	ds_read_b128 v[84:87], v34 offset:512
	ds_read_b128 v[88:91], v34 offset:768
	ds_read_b128 v[92:95], v34 offset:1024
	ds_read_b128 v[96:99], v34 offset:1280
	ds_read_b128 v[100:103], v34 offset:1536
	ds_read_b128 v[104:107], v34 offset:1792
	s_waitcnt lgkmcnt(9)
	v_pk_mul_f32 v[24:25], v[10:11], v[44:45]
	v_pk_fma_f32 v[24:25], v[8:9], v[46:47], v[24:25]
	v_add_f32_e32 v24, v24, v25
	s_waitcnt lgkmcnt(7)
	v_pk_fma_f32 v[16:17], v[76:77], v[156:157], v[10:11] op_sel_hi:[1,0,1]
	v_pk_fma_f32 v[18:19], v[78:79], v[156:157], v[8:9] op_sel_hi:[1,0,1]
	v_add_f32_dpp v15, v24, v24 row_ror:8 row_mask:0xf bank_mask:0xf bound_ctrl:1
	ds_read_b128 v[108:111], v34 offset:2048
	ds_read_b128 v[112:115], v34 offset:2304
	v_add_f32_dpp v15, v15, v15 row_ror:4 row_mask:0xf bank_mask:0xf bound_ctrl:1
	ds_read_b128 v[116:119], v34 offset:2560
	ds_read_b128 v[120:123], v34 offset:2816
	v_add_f32_dpp v15, v15, v15 row_ror:2 row_mask:0xf bank_mask:0xf bound_ctrl:1
	ds_read_b128 v[124:127], v34 offset:3072
	ds_read_b128 v[128:131], v34 offset:3328
	v_add_f32_dpp v30, v15, v15 row_ror:1 row_mask:0xf bank_mask:0xf bound_ctrl:1
	ds_read_b128 v[132:135], v34 offset:3584
	ds_read_b128 v[136:139], v34 offset:3840
	s_waitcnt lgkmcnt(0)
.Lsc_S_loop:
	s_waitcnt lgkmcnt(6)
	v_pk_fma_f32 v[10:11], v[80:81], v[30:31], v[16:17] op_sel_hi:[1,0,1] neg_lo:[0,1,0] neg_hi:[0,1,0]
	v_pk_fma_f32 v[8:9], v[82:83], v[30:31], v[18:19] op_sel_hi:[1,0,1] neg_lo:[0,1,0] neg_hi:[0,1,0]
	v_pk_mul_f32 v[24:25], v[10:11], v[84:85] op_sel:[0,0] op_sel_hi:[0,1]
	v_pk_fma_f32 v[24:25], v[10:11], v[86:87], v[24:25] op_sel:[1,0,0] op_sel_hi:[1,1,1]
	v_pk_fma_f32 v[24:25], v[8:9], v[88:89], v[24:25] op_sel:[0,0,0] op_sel_hi:[0,1,1]
	v_pk_fma_f32 v[24:25], v[8:9], v[90:91], v[24:25] op_sel:[1,0,0] op_sel_hi:[1,1,1]
	v_pk_fma_f32 v[16:17], v[92:93], v[156:157], v[10:11] op_sel:[0,1,0] op_sel_hi:[1,1,1]
	v_pk_fma_f32 v[18:19], v[94:95], v[156:157], v[8:9] op_sel:[0,1,0] op_sel_hi:[1,1,1]
	v_add_f32_dpp v15, v24, v24 row_ror:8 row_mask:0xf bank_mask:0xf bound_ctrl:1
	v_add_f32_dpp v32, v25, v25 row_ror:8 row_mask:0xf bank_mask:0xf bound_ctrl:1
	ds_read_b128 v[76:79], v34 offset:4096
	v_add_f32_dpp v15, v15, v15 row_ror:4 row_mask:0xf bank_mask:0xf bound_ctrl:1
	ds_read_b128 v[80:83], v34 offset:4352
	ds_read_b128 v[84:87], v34 offset:4608
	v_add_f32_dpp v15, v15, v15 row_ror:2 row_mask:0xf bank_mask:0xf bound_ctrl:1
	ds_read_b128 v[88:91], v34 offset:4864
	ds_read_b128 v[160:163], v35 offset:16
	v_add_f32_dpp v30, v15, v15 row_ror:1 row_mask:0xf bank_mask:0xf bound_ctrl:1
	v_pk_fma_f32 v[10:11], v[96:97], v[30:31], v[16:17] op_sel_hi:[1,0,1] neg_lo:[0,1,0] neg_hi:[0,1,0]
	v_pk_fma_f32 v[8:9], v[98:99], v[30:31], v[18:19] op_sel_hi:[1,0,1] neg_lo:[0,1,0] neg_hi:[0,1,0]
	v_pk_mul_f32 v[24:25], v[10:11], v[100:101] op_sel:[0,0] op_sel_hi:[0,1]
	v_pk_fma_f32 v[24:25], v[10:11], v[102:103], v[24:25] op_sel:[1,0,0] op_sel_hi:[1,1,1]
	v_pk_fma_f32 v[24:25], v[8:9], v[104:105], v[24:25] op_sel:[0,0,0] op_sel_hi:[0,1,1]
	v_pk_fma_f32 v[24:25], v[8:9], v[106:107], v[24:25] op_sel:[1,0,0] op_sel_hi:[1,1,1]
	v_pk_fma_f32 v[16:17], v[108:109], v[158:159], v[10:11] op_sel_hi:[1,0,1]
	v_pk_fma_f32 v[18:19], v[110:111], v[158:159], v[8:9] op_sel_hi:[1,0,1]
	v_add_f32_dpp v15, v24, v24 row_ror:8 row_mask:0xf bank_mask:0xf bound_ctrl:1
	v_add_f32_dpp v33, v25, v25 row_ror:8 row_mask:0xf bank_mask:0xf bound_ctrl:1
	ds_read_b128 v[92:95], v34 offset:5120
	v_add_f32_dpp v15, v15, v15 row_ror:4 row_mask:0xf bank_mask:0xf bound_ctrl:1
	ds_read_b128 v[96:99], v34 offset:5376
	ds_read_b128 v[100:103], v34 offset:5632
	v_add_f32_dpp v15, v15, v15 row_ror:2 row_mask:0xf bank_mask:0xf bound_ctrl:1
	ds_read_b128 v[104:107], v34 offset:5888
	s_nop 0
	v_add_f32_dpp v30, v15, v15 row_ror:1 row_mask:0xf bank_mask:0xf bound_ctrl:1
	ds_write2st64_b32 v37, v32, v33 offset0:0 offset1:2
	s_waitcnt lgkmcnt(5)
	v_pk_fma_f32 v[10:11], v[112:113], v[30:31], v[16:17] op_sel_hi:[1,0,1] neg_lo:[0,1,0] neg_hi:[0,1,0]
	v_pk_fma_f32 v[8:9], v[114:115], v[30:31], v[18:19] op_sel_hi:[1,0,1] neg_lo:[0,1,0] neg_hi:[0,1,0]
	v_pk_mul_f32 v[24:25], v[10:11], v[116:117] op_sel:[0,0] op_sel_hi:[0,1]
	v_pk_fma_f32 v[24:25], v[10:11], v[118:119], v[24:25] op_sel:[1,0,0] op_sel_hi:[1,1,1]
	v_pk_fma_f32 v[24:25], v[8:9], v[120:121], v[24:25] op_sel:[0,0,0] op_sel_hi:[0,1,1]
	v_pk_fma_f32 v[24:25], v[8:9], v[122:123], v[24:25] op_sel:[1,0,0] op_sel_hi:[1,1,1]
	v_pk_fma_f32 v[16:17], v[124:125], v[158:159], v[10:11] op_sel:[0,1,0] op_sel_hi:[1,1,1]
	v_pk_fma_f32 v[18:19], v[126:127], v[158:159], v[8:9] op_sel:[0,1,0] op_sel_hi:[1,1,1]
	v_add_f32_dpp v15, v24, v24 row_ror:8 row_mask:0xf bank_mask:0xf bound_ctrl:1
	v_add_f32_dpp v32, v25, v25 row_ror:8 row_mask:0xf bank_mask:0xf bound_ctrl:1
	ds_read_b128 v[108:111], v34 offset:6144
	v_add_f32_dpp v15, v15, v15 row_ror:4 row_mask:0xf bank_mask:0xf bound_ctrl:1
	ds_read_b128 v[112:115], v34 offset:6400
	ds_read_b128 v[116:119], v34 offset:6656
	v_add_f32_dpp v15, v15, v15 row_ror:2 row_mask:0xf bank_mask:0xf bound_ctrl:1
	ds_read_b128 v[120:123], v34 offset:6912
	ds_read_b128 v[40:43], v34 offset:33792
	v_add_f32_dpp v30, v15, v15 row_ror:1 row_mask:0xf bank_mask:0xf bound_ctrl:1
	v_pk_fma_f32 v[10:11], v[128:129], v[30:31], v[16:17] op_sel_hi:[1,0,1] neg_lo:[0,1,0] neg_hi:[0,1,0]
	v_pk_fma_f32 v[8:9], v[130:131], v[30:31], v[18:19] op_sel_hi:[1,0,1] neg_lo:[0,1,0] neg_hi:[0,1,0]
	v_pk_mul_f32 v[24:25], v[10:11], v[132:133] op_sel:[0,0] op_sel_hi:[0,1]
	v_pk_fma_f32 v[24:25], v[10:11], v[134:135], v[24:25] op_sel:[1,0,0] op_sel_hi:[1,1,1]
	v_pk_fma_f32 v[24:25], v[8:9], v[136:137], v[24:25] op_sel:[0,0,0] op_sel_hi:[0,1,1]
	v_pk_fma_f32 v[24:25], v[8:9], v[138:139], v[24:25] op_sel:[1,0,0] op_sel_hi:[1,1,1]
	v_pk_fma_f32 v[16:17], v[76:77], v[160:161], v[10:11] op_sel_hi:[1,0,1]
	v_pk_fma_f32 v[18:19], v[78:79], v[160:161], v[8:9] op_sel_hi:[1,0,1]
	v_add_f32_dpp v15, v24, v24 row_ror:8 row_mask:0xf bank_mask:0xf bound_ctrl:1
	v_add_f32_dpp v33, v25, v25 row_ror:8 row_mask:0xf bank_mask:0xf bound_ctrl:1
	ds_read_b128 v[124:127], v34 offset:7168
	v_add_f32_dpp v15, v15, v15 row_ror:4 row_mask:0xf bank_mask:0xf bound_ctrl:1
	ds_read_b128 v[128:131], v34 offset:7424
	ds_read_b128 v[132:135], v34 offset:7680
	v_add_f32_dpp v15, v15, v15 row_ror:2 row_mask:0xf bank_mask:0xf bound_ctrl:1
	ds_read_b128 v[136:139], v34 offset:7936
	ds_read_b128 v[44:47], v34 offset:33024
	v_add_f32_dpp v30, v15, v15 row_ror:1 row_mask:0xf bank_mask:0xf bound_ctrl:1
	ds_write2st64_b32 v37, v32, v33 offset0:4 offset1:6
	s_waitcnt lgkmcnt(6)
	v_pk_fma_f32 v[10:11], v[80:81], v[30:31], v[16:17] op_sel_hi:[1,0,1] neg_lo:[0,1,0] neg_hi:[0,1,0]
	v_pk_fma_f32 v[8:9], v[82:83], v[30:31], v[18:19] op_sel_hi:[1,0,1] neg_lo:[0,1,0] neg_hi:[0,1,0]
	v_pk_mul_f32 v[24:25], v[10:11], v[84:85] op_sel:[0,0] op_sel_hi:[0,1]
	v_pk_fma_f32 v[24:25], v[10:11], v[86:87], v[24:25] op_sel:[1,0,0] op_sel_hi:[1,1,1]
	v_pk_fma_f32 v[24:25], v[8:9], v[88:89], v[24:25] op_sel:[0,0,0] op_sel_hi:[0,1,1]
	v_pk_fma_f32 v[24:25], v[8:9], v[90:91], v[24:25] op_sel:[1,0,0] op_sel_hi:[1,1,1]
	v_pk_fma_f32 v[16:17], v[92:93], v[160:161], v[10:11] op_sel:[0,1,0] op_sel_hi:[1,1,1]
	v_pk_fma_f32 v[18:19], v[94:95], v[160:161], v[8:9] op_sel:[0,1,0] op_sel_hi:[1,1,1]
	v_add_f32_dpp v15, v24, v24 row_ror:8 row_mask:0xf bank_mask:0xf bound_ctrl:1
	v_add_f32_dpp v32, v25, v25 row_ror:8 row_mask:0xf bank_mask:0xf bound_ctrl:1
	ds_read_b128 v[76:79], v34 offset:8192
	v_add_f32_dpp v15, v15, v15 row_ror:4 row_mask:0xf bank_mask:0xf bound_ctrl:1
	ds_read_b128 v[80:83], v34 offset:8448
	ds_read_b128 v[84:87], v34 offset:8704
	v_add_f32_dpp v15, v15, v15 row_ror:2 row_mask:0xf bank_mask:0xf bound_ctrl:1
	ds_read_b128 v[88:91], v34 offset:8960
	ds_read_b128 v[156:159], v35 offset:32
	v_add_f32_dpp v30, v15, v15 row_ror:1 row_mask:0xf bank_mask:0xf bound_ctrl:1
	v_pk_fma_f32 v[10:11], v[96:97], v[30:31], v[16:17] op_sel_hi:[1,0,1] neg_lo:[0,1,0] neg_hi:[0,1,0]
	v_pk_fma_f32 v[8:9], v[98:99], v[30:31], v[18:19] op_sel_hi:[1,0,1] neg_lo:[0,1,0] neg_hi:[0,1,0]
	v_pk_mul_f32 v[24:25], v[10:11], v[100:101] op_sel:[0,0] op_sel_hi:[0,1]
	v_pk_fma_f32 v[24:25], v[10:11], v[102:103], v[24:25] op_sel:[1,0,0] op_sel_hi:[1,1,1]
	v_pk_fma_f32 v[24:25], v[8:9], v[104:105], v[24:25] op_sel:[0,0,0] op_sel_hi:[0,1,1]
	v_pk_fma_f32 v[24:25], v[8:9], v[106:107], v[24:25] op_sel:[1,0,0] op_sel_hi:[1,1,1]
	v_pk_fma_f32 v[16:17], v[108:109], v[162:163], v[10:11] op_sel_hi:[1,0,1]
	v_pk_fma_f32 v[18:19], v[110:111], v[162:163], v[8:9] op_sel_hi:[1,0,1]
	v_add_f32_dpp v15, v24, v24 row_ror:8 row_mask:0xf bank_mask:0xf bound_ctrl:1
	v_add_f32_dpp v33, v25, v25 row_ror:8 row_mask:0xf bank_mask:0xf bound_ctrl:1
	ds_read_b128 v[92:95], v34 offset:9216
	v_add_f32_dpp v15, v15, v15 row_ror:4 row_mask:0xf bank_mask:0xf bound_ctrl:1
	ds_read_b128 v[96:99], v34 offset:9472
	ds_read_b128 v[100:103], v34 offset:9728
	v_add_f32_dpp v15, v15, v15 row_ror:2 row_mask:0xf bank_mask:0xf bound_ctrl:1
	ds_read_b128 v[104:107], v34 offset:9984
	s_nop 0
	v_add_f32_dpp v30, v15, v15 row_ror:1 row_mask:0xf bank_mask:0xf bound_ctrl:1
	ds_write2st64_b32 v37, v32, v33 offset0:8 offset1:10
	s_waitcnt lgkmcnt(5)
	v_pk_fma_f32 v[10:11], v[112:113], v[30:31], v[16:17] op_sel_hi:[1,0,1] neg_lo:[0,1,0] neg_hi:[0,1,0]
	v_pk_fma_f32 v[8:9], v[114:115], v[30:31], v[18:19] op_sel_hi:[1,0,1] neg_lo:[0,1,0] neg_hi:[0,1,0]
	v_pk_mul_f32 v[24:25], v[10:11], v[116:117] op_sel:[0,0] op_sel_hi:[0,1]
	v_pk_fma_f32 v[24:25], v[10:11], v[118:119], v[24:25] op_sel:[1,0,0] op_sel_hi:[1,1,1]
	v_pk_fma_f32 v[24:25], v[8:9], v[120:121], v[24:25] op_sel:[0,0,0] op_sel_hi:[0,1,1]
	v_pk_fma_f32 v[24:25], v[8:9], v[122:123], v[24:25] op_sel:[1,0,0] op_sel_hi:[1,1,1]
	v_pk_fma_f32 v[16:17], v[124:125], v[162:163], v[10:11] op_sel:[0,1,0] op_sel_hi:[1,1,1]
	v_pk_fma_f32 v[18:19], v[126:127], v[162:163], v[8:9] op_sel:[0,1,0] op_sel_hi:[1,1,1]
	v_add_f32_dpp v15, v24, v24 row_ror:8 row_mask:0xf bank_mask:0xf bound_ctrl:1
	v_add_f32_dpp v32, v25, v25 row_ror:8 row_mask:0xf bank_mask:0xf bound_ctrl:1
	ds_read_b128 v[108:111], v34 offset:10240
	v_add_f32_dpp v15, v15, v15 row_ror:4 row_mask:0xf bank_mask:0xf bound_ctrl:1
	ds_read_b128 v[112:115], v34 offset:10496
	ds_read_b128 v[116:119], v34 offset:10752
	v_add_f32_dpp v15, v15, v15 row_ror:2 row_mask:0xf bank_mask:0xf bound_ctrl:1
	ds_read_b128 v[120:123], v34 offset:11008
	s_nop 0
	v_add_f32_dpp v30, v15, v15 row_ror:1 row_mask:0xf bank_mask:0xf bound_ctrl:1
	v_pk_fma_f32 v[10:11], v[128:129], v[30:31], v[16:17] op_sel_hi:[1,0,1] neg_lo:[0,1,0] neg_hi:[0,1,0]
	v_pk_fma_f32 v[8:9], v[130:131], v[30:31], v[18:19] op_sel_hi:[1,0,1] neg_lo:[0,1,0] neg_hi:[0,1,0]
	v_pk_mul_f32 v[24:25], v[10:11], v[132:133] op_sel:[0,0] op_sel_hi:[0,1]
	v_pk_fma_f32 v[24:25], v[10:11], v[134:135], v[24:25] op_sel:[1,0,0] op_sel_hi:[1,1,1]
	v_pk_fma_f32 v[24:25], v[8:9], v[136:137], v[24:25] op_sel:[0,0,0] op_sel_hi:[0,1,1]
	v_pk_fma_f32 v[24:25], v[8:9], v[138:139], v[24:25] op_sel:[1,0,0] op_sel_hi:[1,1,1]
	s_nop 1
	v_add_f32_dpp v33, v25, v25 row_ror:8 row_mask:0xf bank_mask:0xf bound_ctrl:1
	ds_write2st64_b32 v37, v32, v33 offset0:12 offset1:14
	v_pk_mul_f32 v[10:11], v[10:11], v[40:41]
	v_pk_mul_f32 v[8:9], v[8:9], v[42:43]
	v_pk_mul_f32 v[24:25], v[10:11], v[44:45]
	v_pk_fma_f32 v[24:25], v[8:9], v[46:47], v[24:25]
	v_add_f32_e32 v24, v24, v25
	v_pk_fma_f32 v[16:17], v[76:77], v[156:157], v[10:11] op_sel_hi:[1,0,1]
	v_pk_fma_f32 v[18:19], v[78:79], v[156:157], v[8:9] op_sel_hi:[1,0,1]
	v_add_f32_dpp v15, v24, v24 row_ror:8 row_mask:0xf bank_mask:0xf bound_ctrl:1
	ds_read_b128 v[124:127], v34 offset:11264
	ds_read_b128 v[128:131], v34 offset:11520
	v_add_f32_dpp v15, v15, v15 row_ror:4 row_mask:0xf bank_mask:0xf bound_ctrl:1
	ds_read_b128 v[132:135], v34 offset:11776
	ds_read_b128 v[136:139], v34 offset:12032
	v_add_f32_dpp v15, v15, v15 row_ror:2 row_mask:0xf bank_mask:0xf bound_ctrl:1
	s_nop 1
	v_add_f32_dpp v30, v15, v15 row_ror:1 row_mask:0xf bank_mask:0xf bound_ctrl:1
	s_waitcnt lgkmcnt(5)
	v_pk_fma_f32 v[10:11], v[80:81], v[30:31], v[16:17] op_sel_hi:[1,0,1] neg_lo:[0,1,0] neg_hi:[0,1,0]
	v_pk_fma_f32 v[8:9], v[82:83], v[30:31], v[18:19] op_sel_hi:[1,0,1] neg_lo:[0,1,0] neg_hi:[0,1,0]
	v_pk_mul_f32 v[24:25], v[10:11], v[84:85] op_sel:[0,0] op_sel_hi:[0,1]
	v_pk_fma_f32 v[24:25], v[10:11], v[86:87], v[24:25] op_sel:[1,0,0] op_sel_hi:[1,1,1]
	v_pk_fma_f32 v[24:25], v[8:9], v[88:89], v[24:25] op_sel:[0,0,0] op_sel_hi:[0,1,1]
	v_pk_fma_f32 v[24:25], v[8:9], v[90:91], v[24:25] op_sel:[1,0,0] op_sel_hi:[1,1,1]
	v_pk_fma_f32 v[16:17], v[92:93], v[156:157], v[10:11] op_sel:[0,1,0] op_sel_hi:[1,1,1]
	v_pk_fma_f32 v[18:19], v[94:95], v[156:157], v[8:9] op_sel:[0,1,0] op_sel_hi:[1,1,1]
	v_add_f32_dpp v15, v24, v24 row_ror:8 row_mask:0xf bank_mask:0xf bound_ctrl:1
	v_add_f32_dpp v32, v25, v25 row_ror:8 row_mask:0xf bank_mask:0xf bound_ctrl:1
	ds_read_b128 v[76:79], v34 offset:12288
	v_add_f32_dpp v15, v15, v15 row_ror:4 row_mask:0xf bank_mask:0xf bound_ctrl:1
	ds_read_b128 v[80:83], v34 offset:12544
	ds_read_b128 v[84:87], v34 offset:12800
	v_add_f32_dpp v15, v15, v15 row_ror:2 row_mask:0xf bank_mask:0xf bound_ctrl:1
	ds_read_b128 v[88:91], v34 offset:13056
	ds_read_b128 v[160:163], v35 offset:48
	v_add_f32_dpp v30, v15, v15 row_ror:1 row_mask:0xf bank_mask:0xf bound_ctrl:1
	v_pk_fma_f32 v[10:11], v[96:97], v[30:31], v[16:17] op_sel_hi:[1,0,1] neg_lo:[0,1,0] neg_hi:[0,1,0]
	v_pk_fma_f32 v[8:9], v[98:99], v[30:31], v[18:19] op_sel_hi:[1,0,1] neg_lo:[0,1,0] neg_hi:[0,1,0]
	v_pk_mul_f32 v[24:25], v[10:11], v[100:101] op_sel:[0,0] op_sel_hi:[0,1]
	v_pk_fma_f32 v[24:25], v[10:11], v[102:103], v[24:25] op_sel:[1,0,0] op_sel_hi:[1,1,1]
	v_pk_fma_f32 v[24:25], v[8:9], v[104:105], v[24:25] op_sel:[0,0,0] op_sel_hi:[0,1,1]
	v_pk_fma_f32 v[24:25], v[8:9], v[106:107], v[24:25] op_sel:[1,0,0] op_sel_hi:[1,1,1]
	v_pk_fma_f32 v[16:17], v[108:109], v[158:159], v[10:11] op_sel_hi:[1,0,1]
	v_pk_fma_f32 v[18:19], v[110:111], v[158:159], v[8:9] op_sel_hi:[1,0,1]
	v_add_f32_dpp v15, v24, v24 row_ror:8 row_mask:0xf bank_mask:0xf bound_ctrl:1
	v_add_f32_dpp v33, v25, v25 row_ror:8 row_mask:0xf bank_mask:0xf bound_ctrl:1
	ds_read_b128 v[92:95], v34 offset:13312
	v_add_f32_dpp v15, v15, v15 row_ror:4 row_mask:0xf bank_mask:0xf bound_ctrl:1
	ds_read_b128 v[96:99], v34 offset:13568
	ds_read_b128 v[100:103], v34 offset:13824
	v_add_f32_dpp v15, v15, v15 row_ror:2 row_mask:0xf bank_mask:0xf bound_ctrl:1
	ds_read_b128 v[104:107], v34 offset:14080
	s_nop 0
	v_add_f32_dpp v30, v15, v15 row_ror:1 row_mask:0xf bank_mask:0xf bound_ctrl:1
	ds_write2st64_b32 v37, v32, v33 offset0:16 offset1:18
	s_waitcnt lgkmcnt(5)
	v_pk_fma_f32 v[10:11], v[112:113], v[30:31], v[16:17] op_sel_hi:[1,0,1] neg_lo:[0,1,0] neg_hi:[0,1,0]
	v_pk_fma_f32 v[8:9], v[114:115], v[30:31], v[18:19] op_sel_hi:[1,0,1] neg_lo:[0,1,0] neg_hi:[0,1,0]
	v_pk_mul_f32 v[24:25], v[10:11], v[116:117] op_sel:[0,0] op_sel_hi:[0,1]
	v_pk_fma_f32 v[24:25], v[10:11], v[118:119], v[24:25] op_sel:[1,0,0] op_sel_hi:[1,1,1]
	v_pk_fma_f32 v[24:25], v[8:9], v[120:121], v[24:25] op_sel:[0,0,0] op_sel_hi:[0,1,1]
	v_pk_fma_f32 v[24:25], v[8:9], v[122:123], v[24:25] op_sel:[1,0,0] op_sel_hi:[1,1,1]
	v_pk_fma_f32 v[16:17], v[124:125], v[158:159], v[10:11] op_sel:[0,1,0] op_sel_hi:[1,1,1]
	v_pk_fma_f32 v[18:19], v[126:127], v[158:159], v[8:9] op_sel:[0,1,0] op_sel_hi:[1,1,1]
	v_add_f32_dpp v15, v24, v24 row_ror:8 row_mask:0xf bank_mask:0xf bound_ctrl:1
	v_add_f32_dpp v32, v25, v25 row_ror:8 row_mask:0xf bank_mask:0xf bound_ctrl:1
	ds_read_b128 v[108:111], v34 offset:14336
	v_add_f32_dpp v15, v15, v15 row_ror:4 row_mask:0xf bank_mask:0xf bound_ctrl:1
	ds_read_b128 v[112:115], v34 offset:14592
	ds_read_b128 v[116:119], v34 offset:14848
	v_add_f32_dpp v15, v15, v15 row_ror:2 row_mask:0xf bank_mask:0xf bound_ctrl:1
	ds_read_b128 v[120:123], v34 offset:15104
	ds_read_b128 v[40:43], v34 offset:34048
	v_add_f32_dpp v30, v15, v15 row_ror:1 row_mask:0xf bank_mask:0xf bound_ctrl:1
	v_pk_fma_f32 v[10:11], v[128:129], v[30:31], v[16:17] op_sel_hi:[1,0,1] neg_lo:[0,1,0] neg_hi:[0,1,0]
	v_pk_fma_f32 v[8:9], v[130:131], v[30:31], v[18:19] op_sel_hi:[1,0,1] neg_lo:[0,1,0] neg_hi:[0,1,0]
	v_pk_mul_f32 v[24:25], v[10:11], v[132:133] op_sel:[0,0] op_sel_hi:[0,1]
	v_pk_fma_f32 v[24:25], v[10:11], v[134:135], v[24:25] op_sel:[1,0,0] op_sel_hi:[1,1,1]
	v_pk_fma_f32 v[24:25], v[8:9], v[136:137], v[24:25] op_sel:[0,0,0] op_sel_hi:[0,1,1]
	v_pk_fma_f32 v[24:25], v[8:9], v[138:139], v[24:25] op_sel:[1,0,0] op_sel_hi:[1,1,1]
	v_pk_fma_f32 v[16:17], v[76:77], v[160:161], v[10:11] op_sel_hi:[1,0,1]
	v_pk_fma_f32 v[18:19], v[78:79], v[160:161], v[8:9] op_sel_hi:[1,0,1]
	v_add_f32_dpp v15, v24, v24 row_ror:8 row_mask:0xf bank_mask:0xf bound_ctrl:1
	v_add_f32_dpp v33, v25, v25 row_ror:8 row_mask:0xf bank_mask:0xf bound_ctrl:1
	ds_read_b128 v[124:127], v34 offset:15360
	v_add_f32_dpp v15, v15, v15 row_ror:4 row_mask:0xf bank_mask:0xf bound_ctrl:1
	ds_read_b128 v[128:131], v34 offset:15616
	ds_read_b128 v[132:135], v34 offset:15872
	v_add_f32_dpp v15, v15, v15 row_ror:2 row_mask:0xf bank_mask:0xf bound_ctrl:1
	ds_read_b128 v[136:139], v34 offset:16128
	ds_read_b128 v[44:47], v34 offset:33280
	v_add_f32_dpp v30, v15, v15 row_ror:1 row_mask:0xf bank_mask:0xf bound_ctrl:1
	ds_write2st64_b32 v37, v32, v33 offset0:20 offset1:22
	s_waitcnt lgkmcnt(6)
	v_pk_fma_f32 v[10:11], v[80:81], v[30:31], v[16:17] op_sel_hi:[1,0,1] neg_lo:[0,1,0] neg_hi:[0,1,0]
	v_pk_fma_f32 v[8:9], v[82:83], v[30:31], v[18:19] op_sel_hi:[1,0,1] neg_lo:[0,1,0] neg_hi:[0,1,0]
	v_pk_mul_f32 v[24:25], v[10:11], v[84:85] op_sel:[0,0] op_sel_hi:[0,1]
	v_pk_fma_f32 v[24:25], v[10:11], v[86:87], v[24:25] op_sel:[1,0,0] op_sel_hi:[1,1,1]
	v_pk_fma_f32 v[24:25], v[8:9], v[88:89], v[24:25] op_sel:[0,0,0] op_sel_hi:[0,1,1]
	v_pk_fma_f32 v[24:25], v[8:9], v[90:91], v[24:25] op_sel:[1,0,0] op_sel_hi:[1,1,1]
	v_pk_fma_f32 v[16:17], v[92:93], v[160:161], v[10:11] op_sel:[0,1,0] op_sel_hi:[1,1,1]
	v_pk_fma_f32 v[18:19], v[94:95], v[160:161], v[8:9] op_sel:[0,1,0] op_sel_hi:[1,1,1]
	v_add_f32_dpp v15, v24, v24 row_ror:8 row_mask:0xf bank_mask:0xf bound_ctrl:1
	v_add_f32_dpp v32, v25, v25 row_ror:8 row_mask:0xf bank_mask:0xf bound_ctrl:1
	ds_read_b128 v[76:79], v34 offset:16384
	v_add_f32_dpp v15, v15, v15 row_ror:4 row_mask:0xf bank_mask:0xf bound_ctrl:1
	ds_read_b128 v[80:83], v34 offset:16640
	ds_read_b128 v[84:87], v34 offset:16896
	v_add_f32_dpp v15, v15, v15 row_ror:2 row_mask:0xf bank_mask:0xf bound_ctrl:1
	ds_read_b128 v[88:91], v34 offset:17152
	ds_read_b128 v[156:159], v35 offset:64
	v_add_f32_dpp v30, v15, v15 row_ror:1 row_mask:0xf bank_mask:0xf bound_ctrl:1
	v_pk_fma_f32 v[10:11], v[96:97], v[30:31], v[16:17] op_sel_hi:[1,0,1] neg_lo:[0,1,0] neg_hi:[0,1,0]
	v_pk_fma_f32 v[8:9], v[98:99], v[30:31], v[18:19] op_sel_hi:[1,0,1] neg_lo:[0,1,0] neg_hi:[0,1,0]
	v_pk_mul_f32 v[24:25], v[10:11], v[100:101] op_sel:[0,0] op_sel_hi:[0,1]
	v_pk_fma_f32 v[24:25], v[10:11], v[102:103], v[24:25] op_sel:[1,0,0] op_sel_hi:[1,1,1]
	v_pk_fma_f32 v[24:25], v[8:9], v[104:105], v[24:25] op_sel:[0,0,0] op_sel_hi:[0,1,1]
	v_pk_fma_f32 v[24:25], v[8:9], v[106:107], v[24:25] op_sel:[1,0,0] op_sel_hi:[1,1,1]
	v_pk_fma_f32 v[16:17], v[108:109], v[162:163], v[10:11] op_sel_hi:[1,0,1]
	v_pk_fma_f32 v[18:19], v[110:111], v[162:163], v[8:9] op_sel_hi:[1,0,1]
	v_add_f32_dpp v15, v24, v24 row_ror:8 row_mask:0xf bank_mask:0xf bound_ctrl:1
	v_add_f32_dpp v33, v25, v25 row_ror:8 row_mask:0xf bank_mask:0xf bound_ctrl:1
	ds_read_b128 v[92:95], v34 offset:17408
	v_add_f32_dpp v15, v15, v15 row_ror:4 row_mask:0xf bank_mask:0xf bound_ctrl:1
	ds_read_b128 v[96:99], v34 offset:17664
	ds_read_b128 v[100:103], v34 offset:17920
	v_add_f32_dpp v15, v15, v15 row_ror:2 row_mask:0xf bank_mask:0xf bound_ctrl:1
	ds_read_b128 v[104:107], v34 offset:18176
	s_nop 0
	v_add_f32_dpp v30, v15, v15 row_ror:1 row_mask:0xf bank_mask:0xf bound_ctrl:1
	ds_write2st64_b32 v37, v32, v33 offset0:24 offset1:26
	s_waitcnt lgkmcnt(5)
	v_pk_fma_f32 v[10:11], v[112:113], v[30:31], v[16:17] op_sel_hi:[1,0,1] neg_lo:[0,1,0] neg_hi:[0,1,0]
	v_pk_fma_f32 v[8:9], v[114:115], v[30:31], v[18:19] op_sel_hi:[1,0,1] neg_lo:[0,1,0] neg_hi:[0,1,0]
	v_pk_mul_f32 v[24:25], v[10:11], v[116:117] op_sel:[0,0] op_sel_hi:[0,1]
	v_pk_fma_f32 v[24:25], v[10:11], v[118:119], v[24:25] op_sel:[1,0,0] op_sel_hi:[1,1,1]
	v_pk_fma_f32 v[24:25], v[8:9], v[120:121], v[24:25] op_sel:[0,0,0] op_sel_hi:[0,1,1]
	v_pk_fma_f32 v[24:25], v[8:9], v[122:123], v[24:25] op_sel:[1,0,0] op_sel_hi:[1,1,1]
	v_pk_fma_f32 v[16:17], v[124:125], v[162:163], v[10:11] op_sel:[0,1,0] op_sel_hi:[1,1,1]
	v_pk_fma_f32 v[18:19], v[126:127], v[162:163], v[8:9] op_sel:[0,1,0] op_sel_hi:[1,1,1]
	v_add_f32_dpp v15, v24, v24 row_ror:8 row_mask:0xf bank_mask:0xf bound_ctrl:1
	v_add_f32_dpp v32, v25, v25 row_ror:8 row_mask:0xf bank_mask:0xf bound_ctrl:1
	ds_read_b128 v[108:111], v34 offset:18432
	v_add_f32_dpp v15, v15, v15 row_ror:4 row_mask:0xf bank_mask:0xf bound_ctrl:1
	ds_read_b128 v[112:115], v34 offset:18688
	ds_read_b128 v[116:119], v34 offset:18944
	v_add_f32_dpp v15, v15, v15 row_ror:2 row_mask:0xf bank_mask:0xf bound_ctrl:1
	ds_read_b128 v[120:123], v34 offset:19200
	s_nop 0
	v_add_f32_dpp v30, v15, v15 row_ror:1 row_mask:0xf bank_mask:0xf bound_ctrl:1
	v_pk_fma_f32 v[10:11], v[128:129], v[30:31], v[16:17] op_sel_hi:[1,0,1] neg_lo:[0,1,0] neg_hi:[0,1,0]
	v_pk_fma_f32 v[8:9], v[130:131], v[30:31], v[18:19] op_sel_hi:[1,0,1] neg_lo:[0,1,0] neg_hi:[0,1,0]
	v_pk_mul_f32 v[24:25], v[10:11], v[132:133] op_sel:[0,0] op_sel_hi:[0,1]
	v_pk_fma_f32 v[24:25], v[10:11], v[134:135], v[24:25] op_sel:[1,0,0] op_sel_hi:[1,1,1]
	v_pk_fma_f32 v[24:25], v[8:9], v[136:137], v[24:25] op_sel:[0,0,0] op_sel_hi:[0,1,1]
	v_pk_fma_f32 v[24:25], v[8:9], v[138:139], v[24:25] op_sel:[1,0,0] op_sel_hi:[1,1,1]
	s_nop 1
	v_add_f32_dpp v33, v25, v25 row_ror:8 row_mask:0xf bank_mask:0xf bound_ctrl:1
	ds_write2st64_b32 v37, v32, v33 offset0:28 offset1:30
	v_pk_mul_f32 v[10:11], v[10:11], v[40:41]
	v_pk_mul_f32 v[8:9], v[8:9], v[42:43]
	v_pk_mul_f32 v[24:25], v[10:11], v[44:45]
	v_pk_fma_f32 v[24:25], v[8:9], v[46:47], v[24:25]
	v_add_f32_e32 v24, v24, v25
	v_pk_fma_f32 v[16:17], v[76:77], v[156:157], v[10:11] op_sel_hi:[1,0,1]
	v_pk_fma_f32 v[18:19], v[78:79], v[156:157], v[8:9] op_sel_hi:[1,0,1]
	v_add_f32_dpp v15, v24, v24 row_ror:8 row_mask:0xf bank_mask:0xf bound_ctrl:1
	ds_read_b128 v[124:127], v34 offset:19456
	ds_read_b128 v[128:131], v34 offset:19712
	v_add_f32_dpp v15, v15, v15 row_ror:4 row_mask:0xf bank_mask:0xf bound_ctrl:1
	ds_read_b128 v[132:135], v34 offset:19968
	ds_read_b128 v[136:139], v34 offset:20224
	v_add_f32_dpp v15, v15, v15 row_ror:2 row_mask:0xf bank_mask:0xf bound_ctrl:1
	s_nop 1
	v_add_f32_dpp v30, v15, v15 row_ror:1 row_mask:0xf bank_mask:0xf bound_ctrl:1
	s_waitcnt lgkmcnt(5)
	v_pk_fma_f32 v[10:11], v[80:81], v[30:31], v[16:17] op_sel_hi:[1,0,1] neg_lo:[0,1,0] neg_hi:[0,1,0]
	v_pk_fma_f32 v[8:9], v[82:83], v[30:31], v[18:19] op_sel_hi:[1,0,1] neg_lo:[0,1,0] neg_hi:[0,1,0]
	v_pk_mul_f32 v[24:25], v[10:11], v[84:85] op_sel:[0,0] op_sel_hi:[0,1]
	v_pk_fma_f32 v[24:25], v[10:11], v[86:87], v[24:25] op_sel:[1,0,0] op_sel_hi:[1,1,1]
	v_pk_fma_f32 v[24:25], v[8:9], v[88:89], v[24:25] op_sel:[0,0,0] op_sel_hi:[0,1,1]
	v_pk_fma_f32 v[24:25], v[8:9], v[90:91], v[24:25] op_sel:[1,0,0] op_sel_hi:[1,1,1]
	v_pk_fma_f32 v[16:17], v[92:93], v[156:157], v[10:11] op_sel:[0,1,0] op_sel_hi:[1,1,1]
	v_pk_fma_f32 v[18:19], v[94:95], v[156:157], v[8:9] op_sel:[0,1,0] op_sel_hi:[1,1,1]
	v_add_f32_dpp v15, v24, v24 row_ror:8 row_mask:0xf bank_mask:0xf bound_ctrl:1
	v_add_f32_dpp v32, v25, v25 row_ror:8 row_mask:0xf bank_mask:0xf bound_ctrl:1
	ds_read_b128 v[76:79], v34 offset:20480
	v_add_f32_dpp v15, v15, v15 row_ror:4 row_mask:0xf bank_mask:0xf bound_ctrl:1
	ds_read_b128 v[80:83], v34 offset:20736
	ds_read_b128 v[84:87], v34 offset:20992
	v_add_f32_dpp v15, v15, v15 row_ror:2 row_mask:0xf bank_mask:0xf bound_ctrl:1
	ds_read_b128 v[88:91], v34 offset:21248
	ds_read_b128 v[160:163], v35 offset:80
	v_add_f32_dpp v30, v15, v15 row_ror:1 row_mask:0xf bank_mask:0xf bound_ctrl:1
	v_pk_fma_f32 v[10:11], v[96:97], v[30:31], v[16:17] op_sel_hi:[1,0,1] neg_lo:[0,1,0] neg_hi:[0,1,0]
	v_pk_fma_f32 v[8:9], v[98:99], v[30:31], v[18:19] op_sel_hi:[1,0,1] neg_lo:[0,1,0] neg_hi:[0,1,0]
	v_pk_mul_f32 v[24:25], v[10:11], v[100:101] op_sel:[0,0] op_sel_hi:[0,1]
	v_pk_fma_f32 v[24:25], v[10:11], v[102:103], v[24:25] op_sel:[1,0,0] op_sel_hi:[1,1,1]
	v_pk_fma_f32 v[24:25], v[8:9], v[104:105], v[24:25] op_sel:[0,0,0] op_sel_hi:[0,1,1]
	v_pk_fma_f32 v[24:25], v[8:9], v[106:107], v[24:25] op_sel:[1,0,0] op_sel_hi:[1,1,1]
	v_pk_fma_f32 v[16:17], v[108:109], v[158:159], v[10:11] op_sel_hi:[1,0,1]
	v_pk_fma_f32 v[18:19], v[110:111], v[158:159], v[8:9] op_sel_hi:[1,0,1]
	v_add_f32_dpp v15, v24, v24 row_ror:8 row_mask:0xf bank_mask:0xf bound_ctrl:1
	v_add_f32_dpp v33, v25, v25 row_ror:8 row_mask:0xf bank_mask:0xf bound_ctrl:1
	ds_read_b128 v[92:95], v34 offset:21504
	v_add_f32_dpp v15, v15, v15 row_ror:4 row_mask:0xf bank_mask:0xf bound_ctrl:1
	ds_read_b128 v[96:99], v34 offset:21760
	ds_read_b128 v[100:103], v34 offset:22016
	v_add_f32_dpp v15, v15, v15 row_ror:2 row_mask:0xf bank_mask:0xf bound_ctrl:1
	ds_read_b128 v[104:107], v34 offset:22272
	s_nop 0
	v_add_f32_dpp v30, v15, v15 row_ror:1 row_mask:0xf bank_mask:0xf bound_ctrl:1
	ds_write2st64_b32 v37, v32, v33 offset0:32 offset1:34
	s_waitcnt lgkmcnt(5)
	v_pk_fma_f32 v[10:11], v[112:113], v[30:31], v[16:17] op_sel_hi:[1,0,1] neg_lo:[0,1,0] neg_hi:[0,1,0]
	v_pk_fma_f32 v[8:9], v[114:115], v[30:31], v[18:19] op_sel_hi:[1,0,1] neg_lo:[0,1,0] neg_hi:[0,1,0]
	v_pk_mul_f32 v[24:25], v[10:11], v[116:117] op_sel:[0,0] op_sel_hi:[0,1]
	v_pk_fma_f32 v[24:25], v[10:11], v[118:119], v[24:25] op_sel:[1,0,0] op_sel_hi:[1,1,1]
	v_pk_fma_f32 v[24:25], v[8:9], v[120:121], v[24:25] op_sel:[0,0,0] op_sel_hi:[0,1,1]
	v_pk_fma_f32 v[24:25], v[8:9], v[122:123], v[24:25] op_sel:[1,0,0] op_sel_hi:[1,1,1]
	v_pk_fma_f32 v[16:17], v[124:125], v[158:159], v[10:11] op_sel:[0,1,0] op_sel_hi:[1,1,1]
	v_pk_fma_f32 v[18:19], v[126:127], v[158:159], v[8:9] op_sel:[0,1,0] op_sel_hi:[1,1,1]
	v_add_f32_dpp v15, v24, v24 row_ror:8 row_mask:0xf bank_mask:0xf bound_ctrl:1
	v_add_f32_dpp v32, v25, v25 row_ror:8 row_mask:0xf bank_mask:0xf bound_ctrl:1
	ds_read_b128 v[108:111], v34 offset:22528
	v_add_f32_dpp v15, v15, v15 row_ror:4 row_mask:0xf bank_mask:0xf bound_ctrl:1
	ds_read_b128 v[112:115], v34 offset:22784
	ds_read_b128 v[116:119], v34 offset:23040
	v_add_f32_dpp v15, v15, v15 row_ror:2 row_mask:0xf bank_mask:0xf bound_ctrl:1
	ds_read_b128 v[120:123], v34 offset:23296
	ds_read_b128 v[40:43], v34 offset:34304
	v_add_f32_dpp v30, v15, v15 row_ror:1 row_mask:0xf bank_mask:0xf bound_ctrl:1
	v_pk_fma_f32 v[10:11], v[128:129], v[30:31], v[16:17] op_sel_hi:[1,0,1] neg_lo:[0,1,0] neg_hi:[0,1,0]
	v_pk_fma_f32 v[8:9], v[130:131], v[30:31], v[18:19] op_sel_hi:[1,0,1] neg_lo:[0,1,0] neg_hi:[0,1,0]
	v_pk_mul_f32 v[24:25], v[10:11], v[132:133] op_sel:[0,0] op_sel_hi:[0,1]
	v_pk_fma_f32 v[24:25], v[10:11], v[134:135], v[24:25] op_sel:[1,0,0] op_sel_hi:[1,1,1]
	v_pk_fma_f32 v[24:25], v[8:9], v[136:137], v[24:25] op_sel:[0,0,0] op_sel_hi:[0,1,1]
	v_pk_fma_f32 v[24:25], v[8:9], v[138:139], v[24:25] op_sel:[1,0,0] op_sel_hi:[1,1,1]
	v_pk_fma_f32 v[16:17], v[76:77], v[160:161], v[10:11] op_sel_hi:[1,0,1]
	v_pk_fma_f32 v[18:19], v[78:79], v[160:161], v[8:9] op_sel_hi:[1,0,1]
	v_add_f32_dpp v15, v24, v24 row_ror:8 row_mask:0xf bank_mask:0xf bound_ctrl:1
	v_add_f32_dpp v33, v25, v25 row_ror:8 row_mask:0xf bank_mask:0xf bound_ctrl:1
	ds_read_b128 v[124:127], v34 offset:23552
	v_add_f32_dpp v15, v15, v15 row_ror:4 row_mask:0xf bank_mask:0xf bound_ctrl:1
	ds_read_b128 v[128:131], v34 offset:23808
	ds_read_b128 v[132:135], v34 offset:24064
	v_add_f32_dpp v15, v15, v15 row_ror:2 row_mask:0xf bank_mask:0xf bound_ctrl:1
	ds_read_b128 v[136:139], v34 offset:24320
	ds_read_b128 v[44:47], v34 offset:33536
	v_add_f32_dpp v30, v15, v15 row_ror:1 row_mask:0xf bank_mask:0xf bound_ctrl:1
	ds_write2st64_b32 v37, v32, v33 offset0:36 offset1:38
	s_waitcnt lgkmcnt(6)
	v_pk_fma_f32 v[10:11], v[80:81], v[30:31], v[16:17] op_sel_hi:[1,0,1] neg_lo:[0,1,0] neg_hi:[0,1,0]
	v_pk_fma_f32 v[8:9], v[82:83], v[30:31], v[18:19] op_sel_hi:[1,0,1] neg_lo:[0,1,0] neg_hi:[0,1,0]
	v_pk_mul_f32 v[24:25], v[10:11], v[84:85] op_sel:[0,0] op_sel_hi:[0,1]
	v_pk_fma_f32 v[24:25], v[10:11], v[86:87], v[24:25] op_sel:[1,0,0] op_sel_hi:[1,1,1]
	v_pk_fma_f32 v[24:25], v[8:9], v[88:89], v[24:25] op_sel:[0,0,0] op_sel_hi:[0,1,1]
	v_pk_fma_f32 v[24:25], v[8:9], v[90:91], v[24:25] op_sel:[1,0,0] op_sel_hi:[1,1,1]
	v_pk_fma_f32 v[16:17], v[92:93], v[160:161], v[10:11] op_sel:[0,1,0] op_sel_hi:[1,1,1]
	v_pk_fma_f32 v[18:19], v[94:95], v[160:161], v[8:9] op_sel:[0,1,0] op_sel_hi:[1,1,1]
	v_add_f32_dpp v15, v24, v24 row_ror:8 row_mask:0xf bank_mask:0xf bound_ctrl:1
	v_add_f32_dpp v32, v25, v25 row_ror:8 row_mask:0xf bank_mask:0xf bound_ctrl:1
	ds_read_b128 v[76:79], v34 offset:24576
	v_add_f32_dpp v15, v15, v15 row_ror:4 row_mask:0xf bank_mask:0xf bound_ctrl:1
	ds_read_b128 v[80:83], v34 offset:24832
	ds_read_b128 v[84:87], v34 offset:25088
	v_add_f32_dpp v15, v15, v15 row_ror:2 row_mask:0xf bank_mask:0xf bound_ctrl:1
	ds_read_b128 v[88:91], v34 offset:25344
	ds_read_b128 v[156:159], v35 offset:96
	v_add_f32_dpp v30, v15, v15 row_ror:1 row_mask:0xf bank_mask:0xf bound_ctrl:1
	v_pk_fma_f32 v[10:11], v[96:97], v[30:31], v[16:17] op_sel_hi:[1,0,1] neg_lo:[0,1,0] neg_hi:[0,1,0]
	v_pk_fma_f32 v[8:9], v[98:99], v[30:31], v[18:19] op_sel_hi:[1,0,1] neg_lo:[0,1,0] neg_hi:[0,1,0]
	v_pk_mul_f32 v[24:25], v[10:11], v[100:101] op_sel:[0,0] op_sel_hi:[0,1]
	v_pk_fma_f32 v[24:25], v[10:11], v[102:103], v[24:25] op_sel:[1,0,0] op_sel_hi:[1,1,1]
	v_pk_fma_f32 v[24:25], v[8:9], v[104:105], v[24:25] op_sel:[0,0,0] op_sel_hi:[0,1,1]
	v_pk_fma_f32 v[24:25], v[8:9], v[106:107], v[24:25] op_sel:[1,0,0] op_sel_hi:[1,1,1]
	v_pk_fma_f32 v[16:17], v[108:109], v[162:163], v[10:11] op_sel_hi:[1,0,1]
	v_pk_fma_f32 v[18:19], v[110:111], v[162:163], v[8:9] op_sel_hi:[1,0,1]
	v_add_f32_dpp v15, v24, v24 row_ror:8 row_mask:0xf bank_mask:0xf bound_ctrl:1
	v_add_f32_dpp v33, v25, v25 row_ror:8 row_mask:0xf bank_mask:0xf bound_ctrl:1
	ds_read_b128 v[92:95], v34 offset:25600
	v_add_f32_dpp v15, v15, v15 row_ror:4 row_mask:0xf bank_mask:0xf bound_ctrl:1
	ds_read_b128 v[96:99], v34 offset:25856
	ds_read_b128 v[100:103], v34 offset:26112
	v_add_f32_dpp v15, v15, v15 row_ror:2 row_mask:0xf bank_mask:0xf bound_ctrl:1
	ds_read_b128 v[104:107], v34 offset:26368
	s_nop 0
	v_add_f32_dpp v30, v15, v15 row_ror:1 row_mask:0xf bank_mask:0xf bound_ctrl:1
	ds_write2st64_b32 v37, v32, v33 offset0:40 offset1:42
	s_waitcnt lgkmcnt(5)
	v_pk_fma_f32 v[10:11], v[112:113], v[30:31], v[16:17] op_sel_hi:[1,0,1] neg_lo:[0,1,0] neg_hi:[0,1,0]
	v_pk_fma_f32 v[8:9], v[114:115], v[30:31], v[18:19] op_sel_hi:[1,0,1] neg_lo:[0,1,0] neg_hi:[0,1,0]
	v_pk_mul_f32 v[24:25], v[10:11], v[116:117] op_sel:[0,0] op_sel_hi:[0,1]
	v_pk_fma_f32 v[24:25], v[10:11], v[118:119], v[24:25] op_sel:[1,0,0] op_sel_hi:[1,1,1]
	v_pk_fma_f32 v[24:25], v[8:9], v[120:121], v[24:25] op_sel:[0,0,0] op_sel_hi:[0,1,1]
	v_pk_fma_f32 v[24:25], v[8:9], v[122:123], v[24:25] op_sel:[1,0,0] op_sel_hi:[1,1,1]
	v_pk_fma_f32 v[16:17], v[124:125], v[162:163], v[10:11] op_sel:[0,1,0] op_sel_hi:[1,1,1]
	v_pk_fma_f32 v[18:19], v[126:127], v[162:163], v[8:9] op_sel:[0,1,0] op_sel_hi:[1,1,1]
	v_add_f32_dpp v15, v24, v24 row_ror:8 row_mask:0xf bank_mask:0xf bound_ctrl:1
	v_add_f32_dpp v32, v25, v25 row_ror:8 row_mask:0xf bank_mask:0xf bound_ctrl:1
	ds_read_b128 v[108:111], v34 offset:26624
	v_add_f32_dpp v15, v15, v15 row_ror:4 row_mask:0xf bank_mask:0xf bound_ctrl:1
	ds_read_b128 v[112:115], v34 offset:26880
	ds_read_b128 v[116:119], v34 offset:27136
	v_add_f32_dpp v15, v15, v15 row_ror:2 row_mask:0xf bank_mask:0xf bound_ctrl:1
	ds_read_b128 v[120:123], v34 offset:27392
	s_nop 0
	v_add_f32_dpp v30, v15, v15 row_ror:1 row_mask:0xf bank_mask:0xf bound_ctrl:1
	v_pk_fma_f32 v[10:11], v[128:129], v[30:31], v[16:17] op_sel_hi:[1,0,1] neg_lo:[0,1,0] neg_hi:[0,1,0]
	v_pk_fma_f32 v[8:9], v[130:131], v[30:31], v[18:19] op_sel_hi:[1,0,1] neg_lo:[0,1,0] neg_hi:[0,1,0]
	v_pk_mul_f32 v[24:25], v[10:11], v[132:133] op_sel:[0,0] op_sel_hi:[0,1]
	v_pk_fma_f32 v[24:25], v[10:11], v[134:135], v[24:25] op_sel:[1,0,0] op_sel_hi:[1,1,1]
	v_pk_fma_f32 v[24:25], v[8:9], v[136:137], v[24:25] op_sel:[0,0,0] op_sel_hi:[0,1,1]
	v_pk_fma_f32 v[24:25], v[8:9], v[138:139], v[24:25] op_sel:[1,0,0] op_sel_hi:[1,1,1]
	s_nop 1
	v_add_f32_dpp v33, v25, v25 row_ror:8 row_mask:0xf bank_mask:0xf bound_ctrl:1
	ds_write2st64_b32 v37, v32, v33 offset0:44 offset1:46
	v_pk_mul_f32 v[10:11], v[10:11], v[40:41]
	v_pk_mul_f32 v[8:9], v[8:9], v[42:43]
	v_pk_mul_f32 v[24:25], v[10:11], v[44:45]
	v_pk_fma_f32 v[24:25], v[8:9], v[46:47], v[24:25]
	v_add_f32_e32 v24, v24, v25
	v_pk_fma_f32 v[16:17], v[76:77], v[156:157], v[10:11] op_sel_hi:[1,0,1]
	v_pk_fma_f32 v[18:19], v[78:79], v[156:157], v[8:9] op_sel_hi:[1,0,1]
	v_add_f32_dpp v15, v24, v24 row_ror:8 row_mask:0xf bank_mask:0xf bound_ctrl:1
	ds_read_b128 v[124:127], v34 offset:27648
	ds_read_b128 v[128:131], v34 offset:27904
	v_add_f32_dpp v15, v15, v15 row_ror:4 row_mask:0xf bank_mask:0xf bound_ctrl:1
	ds_read_b128 v[132:135], v34 offset:28160
	ds_read_b128 v[136:139], v34 offset:28416
	v_add_f32_dpp v15, v15, v15 row_ror:2 row_mask:0xf bank_mask:0xf bound_ctrl:1
	s_nop 1
	v_add_f32_dpp v30, v15, v15 row_ror:1 row_mask:0xf bank_mask:0xf bound_ctrl:1
	ds_read_b128 v[56:59], v52
	s_waitcnt lgkmcnt(5)
	v_pk_fma_f32 v[10:11], v[80:81], v[30:31], v[16:17] op_sel_hi:[1,0,1] neg_lo:[0,1,0] neg_hi:[0,1,0]
	v_pk_fma_f32 v[8:9], v[82:83], v[30:31], v[18:19] op_sel_hi:[1,0,1] neg_lo:[0,1,0] neg_hi:[0,1,0]
	v_pk_mul_f32 v[24:25], v[10:11], v[84:85] op_sel:[0,0] op_sel_hi:[0,1]
	v_pk_fma_f32 v[24:25], v[10:11], v[86:87], v[24:25] op_sel:[1,0,0] op_sel_hi:[1,1,1]
	v_pk_fma_f32 v[24:25], v[8:9], v[88:89], v[24:25] op_sel:[0,0,0] op_sel_hi:[0,1,1]
	v_pk_fma_f32 v[24:25], v[8:9], v[90:91], v[24:25] op_sel:[1,0,0] op_sel_hi:[1,1,1]
	v_pk_fma_f32 v[16:17], v[92:93], v[156:157], v[10:11] op_sel:[0,1,0] op_sel_hi:[1,1,1]
	v_pk_fma_f32 v[18:19], v[94:95], v[156:157], v[8:9] op_sel:[0,1,0] op_sel_hi:[1,1,1]
	v_add_f32_dpp v15, v24, v24 row_ror:8 row_mask:0xf bank_mask:0xf bound_ctrl:1
	v_add_f32_dpp v32, v25, v25 row_ror:8 row_mask:0xf bank_mask:0xf bound_ctrl:1
	ds_read_b128 v[76:79], v34 offset:28672
	v_add_f32_dpp v15, v15, v15 row_ror:4 row_mask:0xf bank_mask:0xf bound_ctrl:1
	ds_read_b128 v[80:83], v34 offset:28928
	ds_read_b128 v[84:87], v34 offset:29184
	v_add_f32_dpp v15, v15, v15 row_ror:2 row_mask:0xf bank_mask:0xf bound_ctrl:1
	ds_read_b128 v[88:91], v34 offset:29440
	ds_read_b128 v[160:163], v35 offset:112
	v_add_f32_dpp v30, v15, v15 row_ror:1 row_mask:0xf bank_mask:0xf bound_ctrl:1
	s_waitcnt lgkmcnt(5)
	v_min_u32_e32 v56, v56, v57
	v_min3_u32 v56, v56, v58, v59
	v_pk_fma_f32 v[10:11], v[96:97], v[30:31], v[16:17] op_sel_hi:[1,0,1] neg_lo:[0,1,0] neg_hi:[0,1,0]
	v_pk_fma_f32 v[8:9], v[98:99], v[30:31], v[18:19] op_sel_hi:[1,0,1] neg_lo:[0,1,0] neg_hi:[0,1,0]
	v_pk_mul_f32 v[24:25], v[10:11], v[100:101] op_sel:[0,0] op_sel_hi:[0,1]
	v_pk_fma_f32 v[24:25], v[10:11], v[102:103], v[24:25] op_sel:[1,0,0] op_sel_hi:[1,1,1]
	v_pk_fma_f32 v[24:25], v[8:9], v[104:105], v[24:25] op_sel:[0,0,0] op_sel_hi:[0,1,1]
	v_pk_fma_f32 v[24:25], v[8:9], v[106:107], v[24:25] op_sel:[1,0,0] op_sel_hi:[1,1,1]
	v_pk_fma_f32 v[16:17], v[108:109], v[158:159], v[10:11] op_sel_hi:[1,0,1]
	v_pk_fma_f32 v[18:19], v[110:111], v[158:159], v[8:9] op_sel_hi:[1,0,1]
	v_add_f32_dpp v15, v24, v24 row_ror:8 row_mask:0xf bank_mask:0xf bound_ctrl:1
	v_add_f32_dpp v33, v25, v25 row_ror:8 row_mask:0xf bank_mask:0xf bound_ctrl:1
	ds_read_b128 v[92:95], v34 offset:29696
	v_add_f32_dpp v15, v15, v15 row_ror:4 row_mask:0xf bank_mask:0xf bound_ctrl:1
	ds_read_b128 v[96:99], v34 offset:29952
	ds_read_b128 v[100:103], v34 offset:30208
	v_add_f32_dpp v15, v15, v15 row_ror:2 row_mask:0xf bank_mask:0xf bound_ctrl:1
	ds_read_b128 v[104:107], v34 offset:30464
	s_nop 0
	v_add_f32_dpp v30, v15, v15 row_ror:1 row_mask:0xf bank_mask:0xf bound_ctrl:1
	ds_write2st64_b32 v37, v32, v33 offset0:48 offset1:50
	s_waitcnt lgkmcnt(5)
	v_pk_fma_f32 v[10:11], v[112:113], v[30:31], v[16:17] op_sel_hi:[1,0,1] neg_lo:[0,1,0] neg_hi:[0,1,0]
	v_pk_fma_f32 v[8:9], v[114:115], v[30:31], v[18:19] op_sel_hi:[1,0,1] neg_lo:[0,1,0] neg_hi:[0,1,0]
	v_pk_mul_f32 v[24:25], v[10:11], v[116:117] op_sel:[0,0] op_sel_hi:[0,1]
	v_pk_fma_f32 v[24:25], v[10:11], v[118:119], v[24:25] op_sel:[1,0,0] op_sel_hi:[1,1,1]
	v_pk_fma_f32 v[24:25], v[8:9], v[120:121], v[24:25] op_sel:[0,0,0] op_sel_hi:[0,1,1]
	v_pk_fma_f32 v[24:25], v[8:9], v[122:123], v[24:25] op_sel:[1,0,0] op_sel_hi:[1,1,1]
	v_pk_fma_f32 v[16:17], v[124:125], v[158:159], v[10:11] op_sel:[0,1,0] op_sel_hi:[1,1,1]
	v_pk_fma_f32 v[18:19], v[126:127], v[158:159], v[8:9] op_sel:[0,1,0] op_sel_hi:[1,1,1]
	v_add_f32_dpp v15, v24, v24 row_ror:8 row_mask:0xf bank_mask:0xf bound_ctrl:1
	v_add_f32_dpp v32, v25, v25 row_ror:8 row_mask:0xf bank_mask:0xf bound_ctrl:1
	ds_read_b128 v[108:111], v34 offset:30720
	v_add_f32_dpp v15, v15, v15 row_ror:4 row_mask:0xf bank_mask:0xf bound_ctrl:1
	ds_read_b128 v[112:115], v34 offset:30976
	ds_read_b128 v[116:119], v34 offset:31232
	v_add_f32_dpp v15, v15, v15 row_ror:2 row_mask:0xf bank_mask:0xf bound_ctrl:1
	ds_read_b128 v[120:123], v34 offset:31488
	ds_read_b128 v[40:43], v34 offset:34560
	v_add_f32_dpp v30, v15, v15 row_ror:1 row_mask:0xf bank_mask:0xf bound_ctrl:1
	v_pk_fma_f32 v[10:11], v[128:129], v[30:31], v[16:17] op_sel_hi:[1,0,1] neg_lo:[0,1,0] neg_hi:[0,1,0]
	v_pk_fma_f32 v[8:9], v[130:131], v[30:31], v[18:19] op_sel_hi:[1,0,1] neg_lo:[0,1,0] neg_hi:[0,1,0]
	v_pk_mul_f32 v[24:25], v[10:11], v[132:133] op_sel:[0,0] op_sel_hi:[0,1]
	v_pk_fma_f32 v[24:25], v[10:11], v[134:135], v[24:25] op_sel:[1,0,0] op_sel_hi:[1,1,1]
	v_pk_fma_f32 v[24:25], v[8:9], v[136:137], v[24:25] op_sel:[0,0,0] op_sel_hi:[0,1,1]
	v_pk_fma_f32 v[24:25], v[8:9], v[138:139], v[24:25] op_sel:[1,0,0] op_sel_hi:[1,1,1]
	v_pk_fma_f32 v[16:17], v[76:77], v[160:161], v[10:11] op_sel_hi:[1,0,1]
	v_pk_fma_f32 v[18:19], v[78:79], v[160:161], v[8:9] op_sel_hi:[1,0,1]
	v_add_f32_dpp v15, v24, v24 row_ror:8 row_mask:0xf bank_mask:0xf bound_ctrl:1
	v_add_f32_dpp v33, v25, v25 row_ror:8 row_mask:0xf bank_mask:0xf bound_ctrl:1
	ds_read_b128 v[124:127], v34 offset:31744
	v_add_f32_dpp v15, v15, v15 row_ror:4 row_mask:0xf bank_mask:0xf bound_ctrl:1
	ds_read_b128 v[128:131], v34 offset:32000
	ds_read_b128 v[132:135], v34 offset:32256
	v_add_f32_dpp v15, v15, v15 row_ror:2 row_mask:0xf bank_mask:0xf bound_ctrl:1
	ds_read_b128 v[136:139], v34 offset:32512
	s_nop 0
	v_add_f32_dpp v30, v15, v15 row_ror:1 row_mask:0xf bank_mask:0xf bound_ctrl:1
	ds_write2st64_b32 v37, v32, v33 offset0:52 offset1:54
	v_readfirstlane_b32 s54, v56
	s_add_u32 s64, s6, 2
	s_cmp_lt_u32 s54, s64
	s_cbranch_scc1 .Lss_spin_0
.Lss_ok_0:
	s_waitcnt lgkmcnt(5)
	v_pk_fma_f32 v[10:11], v[80:81], v[30:31], v[16:17] op_sel_hi:[1,0,1] neg_lo:[0,1,0] neg_hi:[0,1,0]
	v_pk_fma_f32 v[8:9], v[82:83], v[30:31], v[18:19] op_sel_hi:[1,0,1] neg_lo:[0,1,0] neg_hi:[0,1,0]
	v_pk_mul_f32 v[24:25], v[10:11], v[84:85] op_sel:[0,0] op_sel_hi:[0,1]
	v_pk_fma_f32 v[24:25], v[10:11], v[86:87], v[24:25] op_sel:[1,0,0] op_sel_hi:[1,1,1]
	v_pk_fma_f32 v[24:25], v[8:9], v[88:89], v[24:25] op_sel:[0,0,0] op_sel_hi:[0,1,1]
	v_pk_fma_f32 v[24:25], v[8:9], v[90:91], v[24:25] op_sel:[1,0,0] op_sel_hi:[1,1,1]
	v_pk_fma_f32 v[16:17], v[92:93], v[160:161], v[10:11] op_sel:[0,1,0] op_sel_hi:[1,1,1]
	v_pk_fma_f32 v[18:19], v[94:95], v[160:161], v[8:9] op_sel:[0,1,0] op_sel_hi:[1,1,1]
	v_add_f32_dpp v15, v24, v24 row_ror:8 row_mask:0xf bank_mask:0xf bound_ctrl:1
	v_add_f32_dpp v32, v25, v25 row_ror:8 row_mask:0xf bank_mask:0xf bound_ctrl:1
	ds_read_b128 v[76:79], v48 offset:0
	v_add_f32_dpp v15, v15, v15 row_ror:4 row_mask:0xf bank_mask:0xf bound_ctrl:1
	ds_read_b128 v[80:83], v48 offset:256
	ds_read_b128 v[84:87], v48 offset:512
	v_add_f32_dpp v15, v15, v15 row_ror:2 row_mask:0xf bank_mask:0xf bound_ctrl:1
	ds_read_b128 v[88:91], v48 offset:768
	ds_read_b128 v[44:47], v48 offset:32768
	v_add_f32_dpp v30, v15, v15 row_ror:1 row_mask:0xf bank_mask:0xf bound_ctrl:1
	v_pk_fma_f32 v[10:11], v[96:97], v[30:31], v[16:17] op_sel_hi:[1,0,1] neg_lo:[0,1,0] neg_hi:[0,1,0]
	v_pk_fma_f32 v[8:9], v[98:99], v[30:31], v[18:19] op_sel_hi:[1,0,1] neg_lo:[0,1,0] neg_hi:[0,1,0]
	v_pk_mul_f32 v[24:25], v[10:11], v[100:101] op_sel:[0,0] op_sel_hi:[0,1]
	v_pk_fma_f32 v[24:25], v[10:11], v[102:103], v[24:25] op_sel:[1,0,0] op_sel_hi:[1,1,1]
	v_pk_fma_f32 v[24:25], v[8:9], v[104:105], v[24:25] op_sel:[0,0,0] op_sel_hi:[0,1,1]
	v_pk_fma_f32 v[24:25], v[8:9], v[106:107], v[24:25] op_sel:[1,0,0] op_sel_hi:[1,1,1]
	v_pk_fma_f32 v[16:17], v[108:109], v[162:163], v[10:11] op_sel_hi:[1,0,1]
	v_pk_fma_f32 v[18:19], v[110:111], v[162:163], v[8:9] op_sel_hi:[1,0,1]
	v_add_f32_dpp v15, v24, v24 row_ror:8 row_mask:0xf bank_mask:0xf bound_ctrl:1
	v_add_f32_dpp v33, v25, v25 row_ror:8 row_mask:0xf bank_mask:0xf bound_ctrl:1
	ds_read_b128 v[92:95], v48 offset:1024
	v_add_f32_dpp v15, v15, v15 row_ror:4 row_mask:0xf bank_mask:0xf bound_ctrl:1
	ds_read_b128 v[96:99], v48 offset:1280
	ds_read_b128 v[100:103], v48 offset:1536
	v_add_f32_dpp v15, v15, v15 row_ror:2 row_mask:0xf bank_mask:0xf bound_ctrl:1
	ds_read_b128 v[104:107], v48 offset:1792
	s_nop 0
	v_add_f32_dpp v30, v15, v15 row_ror:1 row_mask:0xf bank_mask:0xf bound_ctrl:1
	ds_write2st64_b32 v37, v32, v33 offset0:56 offset1:58
	ds_read_b128 v[156:159], v49 offset:0
	s_waitcnt lgkmcnt(6)
	v_pk_fma_f32 v[10:11], v[112:113], v[30:31], v[16:17] op_sel_hi:[1,0,1] neg_lo:[0,1,0] neg_hi:[0,1,0]
	v_pk_fma_f32 v[8:9], v[114:115], v[30:31], v[18:19] op_sel_hi:[1,0,1] neg_lo:[0,1,0] neg_hi:[0,1,0]
	v_pk_mul_f32 v[24:25], v[10:11], v[116:117] op_sel:[0,0] op_sel_hi:[0,1]
	v_pk_fma_f32 v[24:25], v[10:11], v[118:119], v[24:25] op_sel:[1,0,0] op_sel_hi:[1,1,1]
	v_pk_fma_f32 v[24:25], v[8:9], v[120:121], v[24:25] op_sel:[0,0,0] op_sel_hi:[0,1,1]
	v_pk_fma_f32 v[24:25], v[8:9], v[122:123], v[24:25] op_sel:[1,0,0] op_sel_hi:[1,1,1]
	v_pk_fma_f32 v[16:17], v[124:125], v[162:163], v[10:11] op_sel:[0,1,0] op_sel_hi:[1,1,1]
	v_pk_fma_f32 v[18:19], v[126:127], v[162:163], v[8:9] op_sel:[0,1,0] op_sel_hi:[1,1,1]
	v_add_f32_dpp v15, v24, v24 row_ror:8 row_mask:0xf bank_mask:0xf bound_ctrl:1
	v_add_f32_dpp v32, v25, v25 row_ror:8 row_mask:0xf bank_mask:0xf bound_ctrl:1
	ds_read_b128 v[108:111], v48 offset:2048
	v_add_f32_dpp v15, v15, v15 row_ror:4 row_mask:0xf bank_mask:0xf bound_ctrl:1
	ds_read_b128 v[112:115], v48 offset:2304
	ds_read_b128 v[116:119], v48 offset:2560
	v_add_f32_dpp v15, v15, v15 row_ror:2 row_mask:0xf bank_mask:0xf bound_ctrl:1
	ds_read_b128 v[120:123], v48 offset:2816
	s_nop 0
	v_add_f32_dpp v30, v15, v15 row_ror:1 row_mask:0xf bank_mask:0xf bound_ctrl:1
	v_pk_fma_f32 v[10:11], v[128:129], v[30:31], v[16:17] op_sel_hi:[1,0,1] neg_lo:[0,1,0] neg_hi:[0,1,0]
	v_pk_fma_f32 v[8:9], v[130:131], v[30:31], v[18:19] op_sel_hi:[1,0,1] neg_lo:[0,1,0] neg_hi:[0,1,0]
	v_pk_mul_f32 v[24:25], v[10:11], v[132:133] op_sel:[0,0] op_sel_hi:[0,1]
	v_pk_fma_f32 v[24:25], v[10:11], v[134:135], v[24:25] op_sel:[1,0,0] op_sel_hi:[1,1,1]
	v_pk_fma_f32 v[24:25], v[8:9], v[136:137], v[24:25] op_sel:[0,0,0] op_sel_hi:[0,1,1]
	v_pk_fma_f32 v[24:25], v[8:9], v[138:139], v[24:25] op_sel:[1,0,0] op_sel_hi:[1,1,1]
	s_nop 1
	v_add_f32_dpp v33, v25, v25 row_ror:8 row_mask:0xf bank_mask:0xf bound_ctrl:1
	ds_write2st64_b32 v37, v32, v33 offset0:60 offset1:62
	v_pk_mul_f32 v[10:11], v[10:11], v[40:41]
	v_pk_mul_f32 v[8:9], v[8:9], v[42:43]
	v_pk_mul_f32 v[24:25], v[10:11], v[44:45]
	v_pk_fma_f32 v[24:25], v[8:9], v[46:47], v[24:25]
	v_add_f32_e32 v24, v24, v25
	s_waitcnt lgkmcnt(5)
	v_pk_fma_f32 v[16:17], v[76:77], v[156:157], v[10:11] op_sel_hi:[1,0,1]
	v_pk_fma_f32 v[18:19], v[78:79], v[156:157], v[8:9] op_sel_hi:[1,0,1]
	v_add_f32_dpp v15, v24, v24 row_ror:8 row_mask:0xf bank_mask:0xf bound_ctrl:1
	v_add_u32_e32 v51, 1, v51
	s_add_u32 s6, s6, 1
	v_add_f32_dpp v15, v15, v15 row_ror:4 row_mask:0xf bank_mask:0xf bound_ctrl:1
	ds_write_b32 v53, v51
	ds_read_b128 v[124:127], v48 offset:3072
	v_add_f32_dpp v15, v15, v15 row_ror:2 row_mask:0xf bank_mask:0xf bound_ctrl:1
	ds_read_b128 v[128:131], v48 offset:3328
	ds_read_b128 v[132:135], v48 offset:3584
	v_add_f32_dpp v30, v15, v15 row_ror:1 row_mask:0xf bank_mask:0xf bound_ctrl:1
	ds_read_b128 v[136:139], v48 offset:3840
	s_waitcnt lgkmcnt(6)
	v_pk_fma_f32 v[10:11], v[80:81], v[30:31], v[16:17] op_sel_hi:[1,0,1] neg_lo:[0,1,0] neg_hi:[0,1,0]
	v_pk_fma_f32 v[8:9], v[82:83], v[30:31], v[18:19] op_sel_hi:[1,0,1] neg_lo:[0,1,0] neg_hi:[0,1,0]
	v_pk_mul_f32 v[24:25], v[10:11], v[84:85] op_sel:[0,0] op_sel_hi:[0,1]
	v_pk_fma_f32 v[24:25], v[10:11], v[86:87], v[24:25] op_sel:[1,0,0] op_sel_hi:[1,1,1]
	v_pk_fma_f32 v[24:25], v[8:9], v[88:89], v[24:25] op_sel:[0,0,0] op_sel_hi:[0,1,1]
	v_pk_fma_f32 v[24:25], v[8:9], v[90:91], v[24:25] op_sel:[1,0,0] op_sel_hi:[1,1,1]
	v_pk_fma_f32 v[16:17], v[92:93], v[156:157], v[10:11] op_sel:[0,1,0] op_sel_hi:[1,1,1]
	v_pk_fma_f32 v[18:19], v[94:95], v[156:157], v[8:9] op_sel:[0,1,0] op_sel_hi:[1,1,1]
	v_add_f32_dpp v15, v24, v24 row_ror:8 row_mask:0xf bank_mask:0xf bound_ctrl:1
	v_add_f32_dpp v32, v25, v25 row_ror:8 row_mask:0xf bank_mask:0xf bound_ctrl:1
	ds_read_b128 v[76:79], v48 offset:4096
	v_add_f32_dpp v15, v15, v15 row_ror:4 row_mask:0xf bank_mask:0xf bound_ctrl:1
	ds_read_b128 v[80:83], v48 offset:4352
	ds_read_b128 v[84:87], v48 offset:4608
	v_add_f32_dpp v15, v15, v15 row_ror:2 row_mask:0xf bank_mask:0xf bound_ctrl:1
	ds_read_b128 v[88:91], v48 offset:4864
	ds_read_b128 v[160:163], v49 offset:16
	v_add_f32_dpp v30, v15, v15 row_ror:1 row_mask:0xf bank_mask:0xf bound_ctrl:1
	v_pk_fma_f32 v[10:11], v[96:97], v[30:31], v[16:17] op_sel_hi:[1,0,1] neg_lo:[0,1,0] neg_hi:[0,1,0]
	v_pk_fma_f32 v[8:9], v[98:99], v[30:31], v[18:19] op_sel_hi:[1,0,1] neg_lo:[0,1,0] neg_hi:[0,1,0]
	v_pk_mul_f32 v[24:25], v[10:11], v[100:101] op_sel:[0,0] op_sel_hi:[0,1]
	v_pk_fma_f32 v[24:25], v[10:11], v[102:103], v[24:25] op_sel:[1,0,0] op_sel_hi:[1,1,1]
	v_pk_fma_f32 v[24:25], v[8:9], v[104:105], v[24:25] op_sel:[0,0,0] op_sel_hi:[0,1,1]
	v_pk_fma_f32 v[24:25], v[8:9], v[106:107], v[24:25] op_sel:[1,0,0] op_sel_hi:[1,1,1]
	v_pk_fma_f32 v[16:17], v[108:109], v[158:159], v[10:11] op_sel_hi:[1,0,1]
	v_pk_fma_f32 v[18:19], v[110:111], v[158:159], v[8:9] op_sel_hi:[1,0,1]
	v_add_f32_dpp v15, v24, v24 row_ror:8 row_mask:0xf bank_mask:0xf bound_ctrl:1
	v_add_f32_dpp v33, v25, v25 row_ror:8 row_mask:0xf bank_mask:0xf bound_ctrl:1
	ds_read_b128 v[92:95], v48 offset:5120
	v_add_f32_dpp v15, v15, v15 row_ror:4 row_mask:0xf bank_mask:0xf bound_ctrl:1
	ds_read_b128 v[96:99], v48 offset:5376
	ds_read_b128 v[100:103], v48 offset:5632
	v_add_f32_dpp v15, v15, v15 row_ror:2 row_mask:0xf bank_mask:0xf bound_ctrl:1
	ds_read_b128 v[104:107], v48 offset:5888
	s_nop 0
	v_add_f32_dpp v30, v15, v15 row_ror:1 row_mask:0xf bank_mask:0xf bound_ctrl:1
	ds_write2st64_b32 v50, v32, v33 offset0:0 offset1:2
	s_waitcnt lgkmcnt(5)
	v_pk_fma_f32 v[10:11], v[112:113], v[30:31], v[16:17] op_sel_hi:[1,0,1] neg_lo:[0,1,0] neg_hi:[0,1,0]
	v_pk_fma_f32 v[8:9], v[114:115], v[30:31], v[18:19] op_sel_hi:[1,0,1] neg_lo:[0,1,0] neg_hi:[0,1,0]
	v_pk_mul_f32 v[24:25], v[10:11], v[116:117] op_sel:[0,0] op_sel_hi:[0,1]
	v_pk_fma_f32 v[24:25], v[10:11], v[118:119], v[24:25] op_sel:[1,0,0] op_sel_hi:[1,1,1]
	v_pk_fma_f32 v[24:25], v[8:9], v[120:121], v[24:25] op_sel:[0,0,0] op_sel_hi:[0,1,1]
	v_pk_fma_f32 v[24:25], v[8:9], v[122:123], v[24:25] op_sel:[1,0,0] op_sel_hi:[1,1,1]
	v_pk_fma_f32 v[16:17], v[124:125], v[158:159], v[10:11] op_sel:[0,1,0] op_sel_hi:[1,1,1]
	v_pk_fma_f32 v[18:19], v[126:127], v[158:159], v[8:9] op_sel:[0,1,0] op_sel_hi:[1,1,1]
	v_add_f32_dpp v15, v24, v24 row_ror:8 row_mask:0xf bank_mask:0xf bound_ctrl:1
	v_add_f32_dpp v32, v25, v25 row_ror:8 row_mask:0xf bank_mask:0xf bound_ctrl:1
	ds_read_b128 v[108:111], v48 offset:6144
	v_add_f32_dpp v15, v15, v15 row_ror:4 row_mask:0xf bank_mask:0xf bound_ctrl:1
	ds_read_b128 v[112:115], v48 offset:6400
	ds_read_b128 v[116:119], v48 offset:6656
	v_add_f32_dpp v15, v15, v15 row_ror:2 row_mask:0xf bank_mask:0xf bound_ctrl:1
	ds_read_b128 v[120:123], v48 offset:6912
	ds_read_b128 v[40:43], v48 offset:33792
	v_add_f32_dpp v30, v15, v15 row_ror:1 row_mask:0xf bank_mask:0xf bound_ctrl:1
	v_pk_fma_f32 v[10:11], v[128:129], v[30:31], v[16:17] op_sel_hi:[1,0,1] neg_lo:[0,1,0] neg_hi:[0,1,0]
	v_pk_fma_f32 v[8:9], v[130:131], v[30:31], v[18:19] op_sel_hi:[1,0,1] neg_lo:[0,1,0] neg_hi:[0,1,0]
	v_pk_mul_f32 v[24:25], v[10:11], v[132:133] op_sel:[0,0] op_sel_hi:[0,1]
	v_pk_fma_f32 v[24:25], v[10:11], v[134:135], v[24:25] op_sel:[1,0,0] op_sel_hi:[1,1,1]
	v_pk_fma_f32 v[24:25], v[8:9], v[136:137], v[24:25] op_sel:[0,0,0] op_sel_hi:[0,1,1]
	v_pk_fma_f32 v[24:25], v[8:9], v[138:139], v[24:25] op_sel:[1,0,0] op_sel_hi:[1,1,1]
	v_pk_fma_f32 v[16:17], v[76:77], v[160:161], v[10:11] op_sel_hi:[1,0,1]
	v_pk_fma_f32 v[18:19], v[78:79], v[160:161], v[8:9] op_sel_hi:[1,0,1]
	v_add_f32_dpp v15, v24, v24 row_ror:8 row_mask:0xf bank_mask:0xf bound_ctrl:1
	v_add_f32_dpp v33, v25, v25 row_ror:8 row_mask:0xf bank_mask:0xf bound_ctrl:1
	ds_read_b128 v[124:127], v48 offset:7168
	v_add_f32_dpp v15, v15, v15 row_ror:4 row_mask:0xf bank_mask:0xf bound_ctrl:1
	ds_read_b128 v[128:131], v48 offset:7424
	ds_read_b128 v[132:135], v48 offset:7680
	v_add_f32_dpp v15, v15, v15 row_ror:2 row_mask:0xf bank_mask:0xf bound_ctrl:1
	ds_read_b128 v[136:139], v48 offset:7936
	ds_read_b128 v[44:47], v48 offset:33024
	v_add_f32_dpp v30, v15, v15 row_ror:1 row_mask:0xf bank_mask:0xf bound_ctrl:1
	ds_write2st64_b32 v50, v32, v33 offset0:4 offset1:6
	s_waitcnt lgkmcnt(6)
	v_pk_fma_f32 v[10:11], v[80:81], v[30:31], v[16:17] op_sel_hi:[1,0,1] neg_lo:[0,1,0] neg_hi:[0,1,0]
	v_pk_fma_f32 v[8:9], v[82:83], v[30:31], v[18:19] op_sel_hi:[1,0,1] neg_lo:[0,1,0] neg_hi:[0,1,0]
	v_pk_mul_f32 v[24:25], v[10:11], v[84:85] op_sel:[0,0] op_sel_hi:[0,1]
	v_pk_fma_f32 v[24:25], v[10:11], v[86:87], v[24:25] op_sel:[1,0,0] op_sel_hi:[1,1,1]
	v_pk_fma_f32 v[24:25], v[8:9], v[88:89], v[24:25] op_sel:[0,0,0] op_sel_hi:[0,1,1]
	v_pk_fma_f32 v[24:25], v[8:9], v[90:91], v[24:25] op_sel:[1,0,0] op_sel_hi:[1,1,1]
	v_pk_fma_f32 v[16:17], v[92:93], v[160:161], v[10:11] op_sel:[0,1,0] op_sel_hi:[1,1,1]
	v_pk_fma_f32 v[18:19], v[94:95], v[160:161], v[8:9] op_sel:[0,1,0] op_sel_hi:[1,1,1]
	v_add_f32_dpp v15, v24, v24 row_ror:8 row_mask:0xf bank_mask:0xf bound_ctrl:1
	v_add_f32_dpp v32, v25, v25 row_ror:8 row_mask:0xf bank_mask:0xf bound_ctrl:1
	ds_read_b128 v[76:79], v48 offset:8192
	v_add_f32_dpp v15, v15, v15 row_ror:4 row_mask:0xf bank_mask:0xf bound_ctrl:1
	ds_read_b128 v[80:83], v48 offset:8448
	ds_read_b128 v[84:87], v48 offset:8704
	v_add_f32_dpp v15, v15, v15 row_ror:2 row_mask:0xf bank_mask:0xf bound_ctrl:1
	ds_read_b128 v[88:91], v48 offset:8960
	ds_read_b128 v[156:159], v49 offset:32
	v_add_f32_dpp v30, v15, v15 row_ror:1 row_mask:0xf bank_mask:0xf bound_ctrl:1
	v_pk_fma_f32 v[10:11], v[96:97], v[30:31], v[16:17] op_sel_hi:[1,0,1] neg_lo:[0,1,0] neg_hi:[0,1,0]
	v_pk_fma_f32 v[8:9], v[98:99], v[30:31], v[18:19] op_sel_hi:[1,0,1] neg_lo:[0,1,0] neg_hi:[0,1,0]
	v_pk_mul_f32 v[24:25], v[10:11], v[100:101] op_sel:[0,0] op_sel_hi:[0,1]
	v_pk_fma_f32 v[24:25], v[10:11], v[102:103], v[24:25] op_sel:[1,0,0] op_sel_hi:[1,1,1]
	v_pk_fma_f32 v[24:25], v[8:9], v[104:105], v[24:25] op_sel:[0,0,0] op_sel_hi:[0,1,1]
	v_pk_fma_f32 v[24:25], v[8:9], v[106:107], v[24:25] op_sel:[1,0,0] op_sel_hi:[1,1,1]
	v_pk_fma_f32 v[16:17], v[108:109], v[162:163], v[10:11] op_sel_hi:[1,0,1]
	v_pk_fma_f32 v[18:19], v[110:111], v[162:163], v[8:9] op_sel_hi:[1,0,1]
	v_add_f32_dpp v15, v24, v24 row_ror:8 row_mask:0xf bank_mask:0xf bound_ctrl:1
	v_add_f32_dpp v33, v25, v25 row_ror:8 row_mask:0xf bank_mask:0xf bound_ctrl:1
	ds_read_b128 v[92:95], v48 offset:9216
	v_add_f32_dpp v15, v15, v15 row_ror:4 row_mask:0xf bank_mask:0xf bound_ctrl:1
	ds_read_b128 v[96:99], v48 offset:9472
	ds_read_b128 v[100:103], v48 offset:9728
	v_add_f32_dpp v15, v15, v15 row_ror:2 row_mask:0xf bank_mask:0xf bound_ctrl:1
	ds_read_b128 v[104:107], v48 offset:9984
	s_nop 0
	v_add_f32_dpp v30, v15, v15 row_ror:1 row_mask:0xf bank_mask:0xf bound_ctrl:1
	ds_write2st64_b32 v50, v32, v33 offset0:8 offset1:10
	s_waitcnt lgkmcnt(5)
	v_pk_fma_f32 v[10:11], v[112:113], v[30:31], v[16:17] op_sel_hi:[1,0,1] neg_lo:[0,1,0] neg_hi:[0,1,0]
	v_pk_fma_f32 v[8:9], v[114:115], v[30:31], v[18:19] op_sel_hi:[1,0,1] neg_lo:[0,1,0] neg_hi:[0,1,0]
	v_pk_mul_f32 v[24:25], v[10:11], v[116:117] op_sel:[0,0] op_sel_hi:[0,1]
	v_pk_fma_f32 v[24:25], v[10:11], v[118:119], v[24:25] op_sel:[1,0,0] op_sel_hi:[1,1,1]
	v_pk_fma_f32 v[24:25], v[8:9], v[120:121], v[24:25] op_sel:[0,0,0] op_sel_hi:[0,1,1]
	v_pk_fma_f32 v[24:25], v[8:9], v[122:123], v[24:25] op_sel:[1,0,0] op_sel_hi:[1,1,1]
	v_pk_fma_f32 v[16:17], v[124:125], v[162:163], v[10:11] op_sel:[0,1,0] op_sel_hi:[1,1,1]
	v_pk_fma_f32 v[18:19], v[126:127], v[162:163], v[8:9] op_sel:[0,1,0] op_sel_hi:[1,1,1]
	v_add_f32_dpp v15, v24, v24 row_ror:8 row_mask:0xf bank_mask:0xf bound_ctrl:1
	v_add_f32_dpp v32, v25, v25 row_ror:8 row_mask:0xf bank_mask:0xf bound_ctrl:1
	ds_read_b128 v[108:111], v48 offset:10240
	v_add_f32_dpp v15, v15, v15 row_ror:4 row_mask:0xf bank_mask:0xf bound_ctrl:1
	ds_read_b128 v[112:115], v48 offset:10496
	ds_read_b128 v[116:119], v48 offset:10752
	v_add_f32_dpp v15, v15, v15 row_ror:2 row_mask:0xf bank_mask:0xf bound_ctrl:1
	ds_read_b128 v[120:123], v48 offset:11008
	s_nop 0
	v_add_f32_dpp v30, v15, v15 row_ror:1 row_mask:0xf bank_mask:0xf bound_ctrl:1
	v_pk_fma_f32 v[10:11], v[128:129], v[30:31], v[16:17] op_sel_hi:[1,0,1] neg_lo:[0,1,0] neg_hi:[0,1,0]
	v_pk_fma_f32 v[8:9], v[130:131], v[30:31], v[18:19] op_sel_hi:[1,0,1] neg_lo:[0,1,0] neg_hi:[0,1,0]
	v_pk_mul_f32 v[24:25], v[10:11], v[132:133] op_sel:[0,0] op_sel_hi:[0,1]
	v_pk_fma_f32 v[24:25], v[10:11], v[134:135], v[24:25] op_sel:[1,0,0] op_sel_hi:[1,1,1]
	v_pk_fma_f32 v[24:25], v[8:9], v[136:137], v[24:25] op_sel:[0,0,0] op_sel_hi:[0,1,1]
	v_pk_fma_f32 v[24:25], v[8:9], v[138:139], v[24:25] op_sel:[1,0,0] op_sel_hi:[1,1,1]
	s_nop 1
	v_add_f32_dpp v33, v25, v25 row_ror:8 row_mask:0xf bank_mask:0xf bound_ctrl:1
	ds_write2st64_b32 v50, v32, v33 offset0:12 offset1:14
	v_pk_mul_f32 v[10:11], v[10:11], v[40:41]
	v_pk_mul_f32 v[8:9], v[8:9], v[42:43]
	v_pk_mul_f32 v[24:25], v[10:11], v[44:45]
	v_pk_fma_f32 v[24:25], v[8:9], v[46:47], v[24:25]
	v_add_f32_e32 v24, v24, v25
	v_pk_fma_f32 v[16:17], v[76:77], v[156:157], v[10:11] op_sel_hi:[1,0,1]
	v_pk_fma_f32 v[18:19], v[78:79], v[156:157], v[8:9] op_sel_hi:[1,0,1]
	v_add_f32_dpp v15, v24, v24 row_ror:8 row_mask:0xf bank_mask:0xf bound_ctrl:1
	ds_read_b128 v[124:127], v48 offset:11264
	ds_read_b128 v[128:131], v48 offset:11520
	v_add_f32_dpp v15, v15, v15 row_ror:4 row_mask:0xf bank_mask:0xf bound_ctrl:1
	ds_read_b128 v[132:135], v48 offset:11776
	ds_read_b128 v[136:139], v48 offset:12032
	v_add_f32_dpp v15, v15, v15 row_ror:2 row_mask:0xf bank_mask:0xf bound_ctrl:1
	s_nop 1
	v_add_f32_dpp v30, v15, v15 row_ror:1 row_mask:0xf bank_mask:0xf bound_ctrl:1
	s_waitcnt lgkmcnt(5)
	v_pk_fma_f32 v[10:11], v[80:81], v[30:31], v[16:17] op_sel_hi:[1,0,1] neg_lo:[0,1,0] neg_hi:[0,1,0]
	v_pk_fma_f32 v[8:9], v[82:83], v[30:31], v[18:19] op_sel_hi:[1,0,1] neg_lo:[0,1,0] neg_hi:[0,1,0]
	v_pk_mul_f32 v[24:25], v[10:11], v[84:85] op_sel:[0,0] op_sel_hi:[0,1]
	v_pk_fma_f32 v[24:25], v[10:11], v[86:87], v[24:25] op_sel:[1,0,0] op_sel_hi:[1,1,1]
	v_pk_fma_f32 v[24:25], v[8:9], v[88:89], v[24:25] op_sel:[0,0,0] op_sel_hi:[0,1,1]
	v_pk_fma_f32 v[24:25], v[8:9], v[90:91], v[24:25] op_sel:[1,0,0] op_sel_hi:[1,1,1]
	v_pk_fma_f32 v[16:17], v[92:93], v[156:157], v[10:11] op_sel:[0,1,0] op_sel_hi:[1,1,1]
	v_pk_fma_f32 v[18:19], v[94:95], v[156:157], v[8:9] op_sel:[0,1,0] op_sel_hi:[1,1,1]
	v_add_f32_dpp v15, v24, v24 row_ror:8 row_mask:0xf bank_mask:0xf bound_ctrl:1
	v_add_f32_dpp v32, v25, v25 row_ror:8 row_mask:0xf bank_mask:0xf bound_ctrl:1
	ds_read_b128 v[76:79], v48 offset:12288
	v_add_f32_dpp v15, v15, v15 row_ror:4 row_mask:0xf bank_mask:0xf bound_ctrl:1
	ds_read_b128 v[80:83], v48 offset:12544
	ds_read_b128 v[84:87], v48 offset:12800
	v_add_f32_dpp v15, v15, v15 row_ror:2 row_mask:0xf bank_mask:0xf bound_ctrl:1
	ds_read_b128 v[88:91], v48 offset:13056
	ds_read_b128 v[160:163], v49 offset:48
	v_add_f32_dpp v30, v15, v15 row_ror:1 row_mask:0xf bank_mask:0xf bound_ctrl:1
	v_pk_fma_f32 v[10:11], v[96:97], v[30:31], v[16:17] op_sel_hi:[1,0,1] neg_lo:[0,1,0] neg_hi:[0,1,0]
	v_pk_fma_f32 v[8:9], v[98:99], v[30:31], v[18:19] op_sel_hi:[1,0,1] neg_lo:[0,1,0] neg_hi:[0,1,0]
	v_pk_mul_f32 v[24:25], v[10:11], v[100:101] op_sel:[0,0] op_sel_hi:[0,1]
	v_pk_fma_f32 v[24:25], v[10:11], v[102:103], v[24:25] op_sel:[1,0,0] op_sel_hi:[1,1,1]
	v_pk_fma_f32 v[24:25], v[8:9], v[104:105], v[24:25] op_sel:[0,0,0] op_sel_hi:[0,1,1]
	v_pk_fma_f32 v[24:25], v[8:9], v[106:107], v[24:25] op_sel:[1,0,0] op_sel_hi:[1,1,1]
	v_pk_fma_f32 v[16:17], v[108:109], v[158:159], v[10:11] op_sel_hi:[1,0,1]
	v_pk_fma_f32 v[18:19], v[110:111], v[158:159], v[8:9] op_sel_hi:[1,0,1]
	v_add_f32_dpp v15, v24, v24 row_ror:8 row_mask:0xf bank_mask:0xf bound_ctrl:1
	v_add_f32_dpp v33, v25, v25 row_ror:8 row_mask:0xf bank_mask:0xf bound_ctrl:1
	ds_read_b128 v[92:95], v48 offset:13312
	v_add_f32_dpp v15, v15, v15 row_ror:4 row_mask:0xf bank_mask:0xf bound_ctrl:1
	ds_read_b128 v[96:99], v48 offset:13568
	ds_read_b128 v[100:103], v48 offset:13824
	v_add_f32_dpp v15, v15, v15 row_ror:2 row_mask:0xf bank_mask:0xf bound_ctrl:1
	ds_read_b128 v[104:107], v48 offset:14080
	s_nop 0
	v_add_f32_dpp v30, v15, v15 row_ror:1 row_mask:0xf bank_mask:0xf bound_ctrl:1
	ds_write2st64_b32 v50, v32, v33 offset0:16 offset1:18
	s_waitcnt lgkmcnt(5)
	v_pk_fma_f32 v[10:11], v[112:113], v[30:31], v[16:17] op_sel_hi:[1,0,1] neg_lo:[0,1,0] neg_hi:[0,1,0]
	v_pk_fma_f32 v[8:9], v[114:115], v[30:31], v[18:19] op_sel_hi:[1,0,1] neg_lo:[0,1,0] neg_hi:[0,1,0]
	v_pk_mul_f32 v[24:25], v[10:11], v[116:117] op_sel:[0,0] op_sel_hi:[0,1]
	v_pk_fma_f32 v[24:25], v[10:11], v[118:119], v[24:25] op_sel:[1,0,0] op_sel_hi:[1,1,1]
	v_pk_fma_f32 v[24:25], v[8:9], v[120:121], v[24:25] op_sel:[0,0,0] op_sel_hi:[0,1,1]
	v_pk_fma_f32 v[24:25], v[8:9], v[122:123], v[24:25] op_sel:[1,0,0] op_sel_hi:[1,1,1]
	v_pk_fma_f32 v[16:17], v[124:125], v[158:159], v[10:11] op_sel:[0,1,0] op_sel_hi:[1,1,1]
	v_pk_fma_f32 v[18:19], v[126:127], v[158:159], v[8:9] op_sel:[0,1,0] op_sel_hi:[1,1,1]
	v_add_f32_dpp v15, v24, v24 row_ror:8 row_mask:0xf bank_mask:0xf bound_ctrl:1
	v_add_f32_dpp v32, v25, v25 row_ror:8 row_mask:0xf bank_mask:0xf bound_ctrl:1
	ds_read_b128 v[108:111], v48 offset:14336
	v_add_f32_dpp v15, v15, v15 row_ror:4 row_mask:0xf bank_mask:0xf bound_ctrl:1
	ds_read_b128 v[112:115], v48 offset:14592
	ds_read_b128 v[116:119], v48 offset:14848
	v_add_f32_dpp v15, v15, v15 row_ror:2 row_mask:0xf bank_mask:0xf bound_ctrl:1
	ds_read_b128 v[120:123], v48 offset:15104
	ds_read_b128 v[40:43], v48 offset:34048
	v_add_f32_dpp v30, v15, v15 row_ror:1 row_mask:0xf bank_mask:0xf bound_ctrl:1
	v_pk_fma_f32 v[10:11], v[128:129], v[30:31], v[16:17] op_sel_hi:[1,0,1] neg_lo:[0,1,0] neg_hi:[0,1,0]
	v_pk_fma_f32 v[8:9], v[130:131], v[30:31], v[18:19] op_sel_hi:[1,0,1] neg_lo:[0,1,0] neg_hi:[0,1,0]
	v_pk_mul_f32 v[24:25], v[10:11], v[132:133] op_sel:[0,0] op_sel_hi:[0,1]
	v_pk_fma_f32 v[24:25], v[10:11], v[134:135], v[24:25] op_sel:[1,0,0] op_sel_hi:[1,1,1]
	v_pk_fma_f32 v[24:25], v[8:9], v[136:137], v[24:25] op_sel:[0,0,0] op_sel_hi:[0,1,1]
	v_pk_fma_f32 v[24:25], v[8:9], v[138:139], v[24:25] op_sel:[1,0,0] op_sel_hi:[1,1,1]
	v_pk_fma_f32 v[16:17], v[76:77], v[160:161], v[10:11] op_sel_hi:[1,0,1]
	v_pk_fma_f32 v[18:19], v[78:79], v[160:161], v[8:9] op_sel_hi:[1,0,1]
	v_add_f32_dpp v15, v24, v24 row_ror:8 row_mask:0xf bank_mask:0xf bound_ctrl:1
	v_add_f32_dpp v33, v25, v25 row_ror:8 row_mask:0xf bank_mask:0xf bound_ctrl:1
	ds_read_b128 v[124:127], v48 offset:15360
	v_add_f32_dpp v15, v15, v15 row_ror:4 row_mask:0xf bank_mask:0xf bound_ctrl:1
	ds_read_b128 v[128:131], v48 offset:15616
	ds_read_b128 v[132:135], v48 offset:15872
	v_add_f32_dpp v15, v15, v15 row_ror:2 row_mask:0xf bank_mask:0xf bound_ctrl:1
	ds_read_b128 v[136:139], v48 offset:16128
	ds_read_b128 v[44:47], v48 offset:33280
	v_add_f32_dpp v30, v15, v15 row_ror:1 row_mask:0xf bank_mask:0xf bound_ctrl:1
	ds_write2st64_b32 v50, v32, v33 offset0:20 offset1:22
	s_waitcnt lgkmcnt(6)
	v_pk_fma_f32 v[10:11], v[80:81], v[30:31], v[16:17] op_sel_hi:[1,0,1] neg_lo:[0,1,0] neg_hi:[0,1,0]
	v_pk_fma_f32 v[8:9], v[82:83], v[30:31], v[18:19] op_sel_hi:[1,0,1] neg_lo:[0,1,0] neg_hi:[0,1,0]
	v_pk_mul_f32 v[24:25], v[10:11], v[84:85] op_sel:[0,0] op_sel_hi:[0,1]
	v_pk_fma_f32 v[24:25], v[10:11], v[86:87], v[24:25] op_sel:[1,0,0] op_sel_hi:[1,1,1]
	v_pk_fma_f32 v[24:25], v[8:9], v[88:89], v[24:25] op_sel:[0,0,0] op_sel_hi:[0,1,1]
	v_pk_fma_f32 v[24:25], v[8:9], v[90:91], v[24:25] op_sel:[1,0,0] op_sel_hi:[1,1,1]
	v_pk_fma_f32 v[16:17], v[92:93], v[160:161], v[10:11] op_sel:[0,1,0] op_sel_hi:[1,1,1]
	v_pk_fma_f32 v[18:19], v[94:95], v[160:161], v[8:9] op_sel:[0,1,0] op_sel_hi:[1,1,1]
	v_add_f32_dpp v15, v24, v24 row_ror:8 row_mask:0xf bank_mask:0xf bound_ctrl:1
	v_add_f32_dpp v32, v25, v25 row_ror:8 row_mask:0xf bank_mask:0xf bound_ctrl:1
	ds_read_b128 v[76:79], v48 offset:16384
	v_add_f32_dpp v15, v15, v15 row_ror:4 row_mask:0xf bank_mask:0xf bound_ctrl:1
	ds_read_b128 v[80:83], v48 offset:16640
	ds_read_b128 v[84:87], v48 offset:16896
	v_add_f32_dpp v15, v15, v15 row_ror:2 row_mask:0xf bank_mask:0xf bound_ctrl:1
	ds_read_b128 v[88:91], v48 offset:17152
	ds_read_b128 v[156:159], v49 offset:64
	v_add_f32_dpp v30, v15, v15 row_ror:1 row_mask:0xf bank_mask:0xf bound_ctrl:1
	v_pk_fma_f32 v[10:11], v[96:97], v[30:31], v[16:17] op_sel_hi:[1,0,1] neg_lo:[0,1,0] neg_hi:[0,1,0]
	v_pk_fma_f32 v[8:9], v[98:99], v[30:31], v[18:19] op_sel_hi:[1,0,1] neg_lo:[0,1,0] neg_hi:[0,1,0]
	v_pk_mul_f32 v[24:25], v[10:11], v[100:101] op_sel:[0,0] op_sel_hi:[0,1]
	v_pk_fma_f32 v[24:25], v[10:11], v[102:103], v[24:25] op_sel:[1,0,0] op_sel_hi:[1,1,1]
	v_pk_fma_f32 v[24:25], v[8:9], v[104:105], v[24:25] op_sel:[0,0,0] op_sel_hi:[0,1,1]
	v_pk_fma_f32 v[24:25], v[8:9], v[106:107], v[24:25] op_sel:[1,0,0] op_sel_hi:[1,1,1]
	v_pk_fma_f32 v[16:17], v[108:109], v[162:163], v[10:11] op_sel_hi:[1,0,1]
	v_pk_fma_f32 v[18:19], v[110:111], v[162:163], v[8:9] op_sel_hi:[1,0,1]
	v_add_f32_dpp v15, v24, v24 row_ror:8 row_mask:0xf bank_mask:0xf bound_ctrl:1
	v_add_f32_dpp v33, v25, v25 row_ror:8 row_mask:0xf bank_mask:0xf bound_ctrl:1
	ds_read_b128 v[92:95], v48 offset:17408
	v_add_f32_dpp v15, v15, v15 row_ror:4 row_mask:0xf bank_mask:0xf bound_ctrl:1
	ds_read_b128 v[96:99], v48 offset:17664
	ds_read_b128 v[100:103], v48 offset:17920
	v_add_f32_dpp v15, v15, v15 row_ror:2 row_mask:0xf bank_mask:0xf bound_ctrl:1
	ds_read_b128 v[104:107], v48 offset:18176
	s_nop 0
	v_add_f32_dpp v30, v15, v15 row_ror:1 row_mask:0xf bank_mask:0xf bound_ctrl:1
	ds_write2st64_b32 v50, v32, v33 offset0:24 offset1:26
	s_waitcnt lgkmcnt(5)
	v_pk_fma_f32 v[10:11], v[112:113], v[30:31], v[16:17] op_sel_hi:[1,0,1] neg_lo:[0,1,0] neg_hi:[0,1,0]
	v_pk_fma_f32 v[8:9], v[114:115], v[30:31], v[18:19] op_sel_hi:[1,0,1] neg_lo:[0,1,0] neg_hi:[0,1,0]
	v_pk_mul_f32 v[24:25], v[10:11], v[116:117] op_sel:[0,0] op_sel_hi:[0,1]
	v_pk_fma_f32 v[24:25], v[10:11], v[118:119], v[24:25] op_sel:[1,0,0] op_sel_hi:[1,1,1]
	v_pk_fma_f32 v[24:25], v[8:9], v[120:121], v[24:25] op_sel:[0,0,0] op_sel_hi:[0,1,1]
	v_pk_fma_f32 v[24:25], v[8:9], v[122:123], v[24:25] op_sel:[1,0,0] op_sel_hi:[1,1,1]
	v_pk_fma_f32 v[16:17], v[124:125], v[162:163], v[10:11] op_sel:[0,1,0] op_sel_hi:[1,1,1]
	v_pk_fma_f32 v[18:19], v[126:127], v[162:163], v[8:9] op_sel:[0,1,0] op_sel_hi:[1,1,1]
	v_add_f32_dpp v15, v24, v24 row_ror:8 row_mask:0xf bank_mask:0xf bound_ctrl:1
	v_add_f32_dpp v32, v25, v25 row_ror:8 row_mask:0xf bank_mask:0xf bound_ctrl:1
	ds_read_b128 v[108:111], v48 offset:18432
	v_add_f32_dpp v15, v15, v15 row_ror:4 row_mask:0xf bank_mask:0xf bound_ctrl:1
	ds_read_b128 v[112:115], v48 offset:18688
	ds_read_b128 v[116:119], v48 offset:18944
	v_add_f32_dpp v15, v15, v15 row_ror:2 row_mask:0xf bank_mask:0xf bound_ctrl:1
	ds_read_b128 v[120:123], v48 offset:19200
	s_nop 0
	v_add_f32_dpp v30, v15, v15 row_ror:1 row_mask:0xf bank_mask:0xf bound_ctrl:1
	v_pk_fma_f32 v[10:11], v[128:129], v[30:31], v[16:17] op_sel_hi:[1,0,1] neg_lo:[0,1,0] neg_hi:[0,1,0]
	v_pk_fma_f32 v[8:9], v[130:131], v[30:31], v[18:19] op_sel_hi:[1,0,1] neg_lo:[0,1,0] neg_hi:[0,1,0]
	v_pk_mul_f32 v[24:25], v[10:11], v[132:133] op_sel:[0,0] op_sel_hi:[0,1]
	v_pk_fma_f32 v[24:25], v[10:11], v[134:135], v[24:25] op_sel:[1,0,0] op_sel_hi:[1,1,1]
	v_pk_fma_f32 v[24:25], v[8:9], v[136:137], v[24:25] op_sel:[0,0,0] op_sel_hi:[0,1,1]
	v_pk_fma_f32 v[24:25], v[8:9], v[138:139], v[24:25] op_sel:[1,0,0] op_sel_hi:[1,1,1]
	s_nop 1
	v_add_f32_dpp v33, v25, v25 row_ror:8 row_mask:0xf bank_mask:0xf bound_ctrl:1
	ds_write2st64_b32 v50, v32, v33 offset0:28 offset1:30
	v_pk_mul_f32 v[10:11], v[10:11], v[40:41]
	v_pk_mul_f32 v[8:9], v[8:9], v[42:43]
	v_pk_mul_f32 v[24:25], v[10:11], v[44:45]
	v_pk_fma_f32 v[24:25], v[8:9], v[46:47], v[24:25]
	v_add_f32_e32 v24, v24, v25
	v_pk_fma_f32 v[16:17], v[76:77], v[156:157], v[10:11] op_sel_hi:[1,0,1]
	v_pk_fma_f32 v[18:19], v[78:79], v[156:157], v[8:9] op_sel_hi:[1,0,1]
	v_add_f32_dpp v15, v24, v24 row_ror:8 row_mask:0xf bank_mask:0xf bound_ctrl:1
	ds_read_b128 v[124:127], v48 offset:19456
	ds_read_b128 v[128:131], v48 offset:19712
	v_add_f32_dpp v15, v15, v15 row_ror:4 row_mask:0xf bank_mask:0xf bound_ctrl:1
	ds_read_b128 v[132:135], v48 offset:19968
	ds_read_b128 v[136:139], v48 offset:20224
	v_add_f32_dpp v15, v15, v15 row_ror:2 row_mask:0xf bank_mask:0xf bound_ctrl:1
	s_nop 1
	v_add_f32_dpp v30, v15, v15 row_ror:1 row_mask:0xf bank_mask:0xf bound_ctrl:1
	s_waitcnt lgkmcnt(5)
	v_pk_fma_f32 v[10:11], v[80:81], v[30:31], v[16:17] op_sel_hi:[1,0,1] neg_lo:[0,1,0] neg_hi:[0,1,0]
	v_pk_fma_f32 v[8:9], v[82:83], v[30:31], v[18:19] op_sel_hi:[1,0,1] neg_lo:[0,1,0] neg_hi:[0,1,0]
	v_pk_mul_f32 v[24:25], v[10:11], v[84:85] op_sel:[0,0] op_sel_hi:[0,1]
	v_pk_fma_f32 v[24:25], v[10:11], v[86:87], v[24:25] op_sel:[1,0,0] op_sel_hi:[1,1,1]
	v_pk_fma_f32 v[24:25], v[8:9], v[88:89], v[24:25] op_sel:[0,0,0] op_sel_hi:[0,1,1]
	v_pk_fma_f32 v[24:25], v[8:9], v[90:91], v[24:25] op_sel:[1,0,0] op_sel_hi:[1,1,1]
	v_pk_fma_f32 v[16:17], v[92:93], v[156:157], v[10:11] op_sel:[0,1,0] op_sel_hi:[1,1,1]
	v_pk_fma_f32 v[18:19], v[94:95], v[156:157], v[8:9] op_sel:[0,1,0] op_sel_hi:[1,1,1]
	v_add_f32_dpp v15, v24, v24 row_ror:8 row_mask:0xf bank_mask:0xf bound_ctrl:1
	v_add_f32_dpp v32, v25, v25 row_ror:8 row_mask:0xf bank_mask:0xf bound_ctrl:1
	ds_read_b128 v[76:79], v48 offset:20480
	v_add_f32_dpp v15, v15, v15 row_ror:4 row_mask:0xf bank_mask:0xf bound_ctrl:1
	ds_read_b128 v[80:83], v48 offset:20736
	ds_read_b128 v[84:87], v48 offset:20992
	v_add_f32_dpp v15, v15, v15 row_ror:2 row_mask:0xf bank_mask:0xf bound_ctrl:1
	ds_read_b128 v[88:91], v48 offset:21248
	ds_read_b128 v[160:163], v49 offset:80
	v_add_f32_dpp v30, v15, v15 row_ror:1 row_mask:0xf bank_mask:0xf bound_ctrl:1
	v_pk_fma_f32 v[10:11], v[96:97], v[30:31], v[16:17] op_sel_hi:[1,0,1] neg_lo:[0,1,0] neg_hi:[0,1,0]
	v_pk_fma_f32 v[8:9], v[98:99], v[30:31], v[18:19] op_sel_hi:[1,0,1] neg_lo:[0,1,0] neg_hi:[0,1,0]
	v_pk_mul_f32 v[24:25], v[10:11], v[100:101] op_sel:[0,0] op_sel_hi:[0,1]
	v_pk_fma_f32 v[24:25], v[10:11], v[102:103], v[24:25] op_sel:[1,0,0] op_sel_hi:[1,1,1]
	v_pk_fma_f32 v[24:25], v[8:9], v[104:105], v[24:25] op_sel:[0,0,0] op_sel_hi:[0,1,1]
	v_pk_fma_f32 v[24:25], v[8:9], v[106:107], v[24:25] op_sel:[1,0,0] op_sel_hi:[1,1,1]
	v_pk_fma_f32 v[16:17], v[108:109], v[158:159], v[10:11] op_sel_hi:[1,0,1]
	v_pk_fma_f32 v[18:19], v[110:111], v[158:159], v[8:9] op_sel_hi:[1,0,1]
	v_add_f32_dpp v15, v24, v24 row_ror:8 row_mask:0xf bank_mask:0xf bound_ctrl:1
	v_add_f32_dpp v33, v25, v25 row_ror:8 row_mask:0xf bank_mask:0xf bound_ctrl:1
	ds_read_b128 v[92:95], v48 offset:21504
	v_add_f32_dpp v15, v15, v15 row_ror:4 row_mask:0xf bank_mask:0xf bound_ctrl:1
	ds_read_b128 v[96:99], v48 offset:21760
	ds_read_b128 v[100:103], v48 offset:22016
	v_add_f32_dpp v15, v15, v15 row_ror:2 row_mask:0xf bank_mask:0xf bound_ctrl:1
	ds_read_b128 v[104:107], v48 offset:22272
	s_nop 0
	v_add_f32_dpp v30, v15, v15 row_ror:1 row_mask:0xf bank_mask:0xf bound_ctrl:1
	ds_write2st64_b32 v50, v32, v33 offset0:32 offset1:34
	s_waitcnt lgkmcnt(5)
	v_pk_fma_f32 v[10:11], v[112:113], v[30:31], v[16:17] op_sel_hi:[1,0,1] neg_lo:[0,1,0] neg_hi:[0,1,0]
	v_pk_fma_f32 v[8:9], v[114:115], v[30:31], v[18:19] op_sel_hi:[1,0,1] neg_lo:[0,1,0] neg_hi:[0,1,0]
	v_pk_mul_f32 v[24:25], v[10:11], v[116:117] op_sel:[0,0] op_sel_hi:[0,1]
	v_pk_fma_f32 v[24:25], v[10:11], v[118:119], v[24:25] op_sel:[1,0,0] op_sel_hi:[1,1,1]
	v_pk_fma_f32 v[24:25], v[8:9], v[120:121], v[24:25] op_sel:[0,0,0] op_sel_hi:[0,1,1]
	v_pk_fma_f32 v[24:25], v[8:9], v[122:123], v[24:25] op_sel:[1,0,0] op_sel_hi:[1,1,1]
	v_pk_fma_f32 v[16:17], v[124:125], v[158:159], v[10:11] op_sel:[0,1,0] op_sel_hi:[1,1,1]
	v_pk_fma_f32 v[18:19], v[126:127], v[158:159], v[8:9] op_sel:[0,1,0] op_sel_hi:[1,1,1]
	v_add_f32_dpp v15, v24, v24 row_ror:8 row_mask:0xf bank_mask:0xf bound_ctrl:1
	v_add_f32_dpp v32, v25, v25 row_ror:8 row_mask:0xf bank_mask:0xf bound_ctrl:1
	ds_read_b128 v[108:111], v48 offset:22528
	v_add_f32_dpp v15, v15, v15 row_ror:4 row_mask:0xf bank_mask:0xf bound_ctrl:1
	ds_read_b128 v[112:115], v48 offset:22784
	ds_read_b128 v[116:119], v48 offset:23040
	v_add_f32_dpp v15, v15, v15 row_ror:2 row_mask:0xf bank_mask:0xf bound_ctrl:1
	ds_read_b128 v[120:123], v48 offset:23296
	ds_read_b128 v[40:43], v48 offset:34304
	v_add_f32_dpp v30, v15, v15 row_ror:1 row_mask:0xf bank_mask:0xf bound_ctrl:1
	v_pk_fma_f32 v[10:11], v[128:129], v[30:31], v[16:17] op_sel_hi:[1,0,1] neg_lo:[0,1,0] neg_hi:[0,1,0]
	v_pk_fma_f32 v[8:9], v[130:131], v[30:31], v[18:19] op_sel_hi:[1,0,1] neg_lo:[0,1,0] neg_hi:[0,1,0]
	v_pk_mul_f32 v[24:25], v[10:11], v[132:133] op_sel:[0,0] op_sel_hi:[0,1]
	v_pk_fma_f32 v[24:25], v[10:11], v[134:135], v[24:25] op_sel:[1,0,0] op_sel_hi:[1,1,1]
	v_pk_fma_f32 v[24:25], v[8:9], v[136:137], v[24:25] op_sel:[0,0,0] op_sel_hi:[0,1,1]
	v_pk_fma_f32 v[24:25], v[8:9], v[138:139], v[24:25] op_sel:[1,0,0] op_sel_hi:[1,1,1]
	v_pk_fma_f32 v[16:17], v[76:77], v[160:161], v[10:11] op_sel_hi:[1,0,1]
	v_pk_fma_f32 v[18:19], v[78:79], v[160:161], v[8:9] op_sel_hi:[1,0,1]
	v_add_f32_dpp v15, v24, v24 row_ror:8 row_mask:0xf bank_mask:0xf bound_ctrl:1
	v_add_f32_dpp v33, v25, v25 row_ror:8 row_mask:0xf bank_mask:0xf bound_ctrl:1
	ds_read_b128 v[124:127], v48 offset:23552
	v_add_f32_dpp v15, v15, v15 row_ror:4 row_mask:0xf bank_mask:0xf bound_ctrl:1
	ds_read_b128 v[128:131], v48 offset:23808
	ds_read_b128 v[132:135], v48 offset:24064
	v_add_f32_dpp v15, v15, v15 row_ror:2 row_mask:0xf bank_mask:0xf bound_ctrl:1
	ds_read_b128 v[136:139], v48 offset:24320
	ds_read_b128 v[44:47], v48 offset:33536
	v_add_f32_dpp v30, v15, v15 row_ror:1 row_mask:0xf bank_mask:0xf bound_ctrl:1
	ds_write2st64_b32 v50, v32, v33 offset0:36 offset1:38
	s_waitcnt lgkmcnt(6)
	v_pk_fma_f32 v[10:11], v[80:81], v[30:31], v[16:17] op_sel_hi:[1,0,1] neg_lo:[0,1,0] neg_hi:[0,1,0]
	v_pk_fma_f32 v[8:9], v[82:83], v[30:31], v[18:19] op_sel_hi:[1,0,1] neg_lo:[0,1,0] neg_hi:[0,1,0]
	v_pk_mul_f32 v[24:25], v[10:11], v[84:85] op_sel:[0,0] op_sel_hi:[0,1]
	v_pk_fma_f32 v[24:25], v[10:11], v[86:87], v[24:25] op_sel:[1,0,0] op_sel_hi:[1,1,1]
	v_pk_fma_f32 v[24:25], v[8:9], v[88:89], v[24:25] op_sel:[0,0,0] op_sel_hi:[0,1,1]
	v_pk_fma_f32 v[24:25], v[8:9], v[90:91], v[24:25] op_sel:[1,0,0] op_sel_hi:[1,1,1]
	v_pk_fma_f32 v[16:17], v[92:93], v[160:161], v[10:11] op_sel:[0,1,0] op_sel_hi:[1,1,1]
	v_pk_fma_f32 v[18:19], v[94:95], v[160:161], v[8:9] op_sel:[0,1,0] op_sel_hi:[1,1,1]
	v_add_f32_dpp v15, v24, v24 row_ror:8 row_mask:0xf bank_mask:0xf bound_ctrl:1
	v_add_f32_dpp v32, v25, v25 row_ror:8 row_mask:0xf bank_mask:0xf bound_ctrl:1
	ds_read_b128 v[76:79], v48 offset:24576
	v_add_f32_dpp v15, v15, v15 row_ror:4 row_mask:0xf bank_mask:0xf bound_ctrl:1
	ds_read_b128 v[80:83], v48 offset:24832
	ds_read_b128 v[84:87], v48 offset:25088
	v_add_f32_dpp v15, v15, v15 row_ror:2 row_mask:0xf bank_mask:0xf bound_ctrl:1
	ds_read_b128 v[88:91], v48 offset:25344
	ds_read_b128 v[156:159], v49 offset:96
	v_add_f32_dpp v30, v15, v15 row_ror:1 row_mask:0xf bank_mask:0xf bound_ctrl:1
	v_pk_fma_f32 v[10:11], v[96:97], v[30:31], v[16:17] op_sel_hi:[1,0,1] neg_lo:[0,1,0] neg_hi:[0,1,0]
	v_pk_fma_f32 v[8:9], v[98:99], v[30:31], v[18:19] op_sel_hi:[1,0,1] neg_lo:[0,1,0] neg_hi:[0,1,0]
	v_pk_mul_f32 v[24:25], v[10:11], v[100:101] op_sel:[0,0] op_sel_hi:[0,1]
	v_pk_fma_f32 v[24:25], v[10:11], v[102:103], v[24:25] op_sel:[1,0,0] op_sel_hi:[1,1,1]
	v_pk_fma_f32 v[24:25], v[8:9], v[104:105], v[24:25] op_sel:[0,0,0] op_sel_hi:[0,1,1]
	v_pk_fma_f32 v[24:25], v[8:9], v[106:107], v[24:25] op_sel:[1,0,0] op_sel_hi:[1,1,1]
	v_pk_fma_f32 v[16:17], v[108:109], v[162:163], v[10:11] op_sel_hi:[1,0,1]
	v_pk_fma_f32 v[18:19], v[110:111], v[162:163], v[8:9] op_sel_hi:[1,0,1]
	v_add_f32_dpp v15, v24, v24 row_ror:8 row_mask:0xf bank_mask:0xf bound_ctrl:1
	v_add_f32_dpp v33, v25, v25 row_ror:8 row_mask:0xf bank_mask:0xf bound_ctrl:1
	ds_read_b128 v[92:95], v48 offset:25600
	v_add_f32_dpp v15, v15, v15 row_ror:4 row_mask:0xf bank_mask:0xf bound_ctrl:1
	ds_read_b128 v[96:99], v48 offset:25856
	ds_read_b128 v[100:103], v48 offset:26112
	v_add_f32_dpp v15, v15, v15 row_ror:2 row_mask:0xf bank_mask:0xf bound_ctrl:1
	ds_read_b128 v[104:107], v48 offset:26368
	s_nop 0
	v_add_f32_dpp v30, v15, v15 row_ror:1 row_mask:0xf bank_mask:0xf bound_ctrl:1
	ds_write2st64_b32 v50, v32, v33 offset0:40 offset1:42
	s_waitcnt lgkmcnt(5)
	v_pk_fma_f32 v[10:11], v[112:113], v[30:31], v[16:17] op_sel_hi:[1,0,1] neg_lo:[0,1,0] neg_hi:[0,1,0]
	v_pk_fma_f32 v[8:9], v[114:115], v[30:31], v[18:19] op_sel_hi:[1,0,1] neg_lo:[0,1,0] neg_hi:[0,1,0]
	v_pk_mul_f32 v[24:25], v[10:11], v[116:117] op_sel:[0,0] op_sel_hi:[0,1]
	v_pk_fma_f32 v[24:25], v[10:11], v[118:119], v[24:25] op_sel:[1,0,0] op_sel_hi:[1,1,1]
	v_pk_fma_f32 v[24:25], v[8:9], v[120:121], v[24:25] op_sel:[0,0,0] op_sel_hi:[0,1,1]
	v_pk_fma_f32 v[24:25], v[8:9], v[122:123], v[24:25] op_sel:[1,0,0] op_sel_hi:[1,1,1]
	v_pk_fma_f32 v[16:17], v[124:125], v[162:163], v[10:11] op_sel:[0,1,0] op_sel_hi:[1,1,1]
	v_pk_fma_f32 v[18:19], v[126:127], v[162:163], v[8:9] op_sel:[0,1,0] op_sel_hi:[1,1,1]
	v_add_f32_dpp v15, v24, v24 row_ror:8 row_mask:0xf bank_mask:0xf bound_ctrl:1
	v_add_f32_dpp v32, v25, v25 row_ror:8 row_mask:0xf bank_mask:0xf bound_ctrl:1
	ds_read_b128 v[108:111], v48 offset:26624
	v_add_f32_dpp v15, v15, v15 row_ror:4 row_mask:0xf bank_mask:0xf bound_ctrl:1
	ds_read_b128 v[112:115], v48 offset:26880
	ds_read_b128 v[116:119], v48 offset:27136
	v_add_f32_dpp v15, v15, v15 row_ror:2 row_mask:0xf bank_mask:0xf bound_ctrl:1
	ds_read_b128 v[120:123], v48 offset:27392
	s_nop 0
	v_add_f32_dpp v30, v15, v15 row_ror:1 row_mask:0xf bank_mask:0xf bound_ctrl:1
	v_pk_fma_f32 v[10:11], v[128:129], v[30:31], v[16:17] op_sel_hi:[1,0,1] neg_lo:[0,1,0] neg_hi:[0,1,0]
	v_pk_fma_f32 v[8:9], v[130:131], v[30:31], v[18:19] op_sel_hi:[1,0,1] neg_lo:[0,1,0] neg_hi:[0,1,0]
	v_pk_mul_f32 v[24:25], v[10:11], v[132:133] op_sel:[0,0] op_sel_hi:[0,1]
	v_pk_fma_f32 v[24:25], v[10:11], v[134:135], v[24:25] op_sel:[1,0,0] op_sel_hi:[1,1,1]
	v_pk_fma_f32 v[24:25], v[8:9], v[136:137], v[24:25] op_sel:[0,0,0] op_sel_hi:[0,1,1]
	v_pk_fma_f32 v[24:25], v[8:9], v[138:139], v[24:25] op_sel:[1,0,0] op_sel_hi:[1,1,1]
	s_nop 1
	v_add_f32_dpp v33, v25, v25 row_ror:8 row_mask:0xf bank_mask:0xf bound_ctrl:1
	ds_write2st64_b32 v50, v32, v33 offset0:44 offset1:46
	v_pk_mul_f32 v[10:11], v[10:11], v[40:41]
	v_pk_mul_f32 v[8:9], v[8:9], v[42:43]
	v_pk_mul_f32 v[24:25], v[10:11], v[44:45]
	v_pk_fma_f32 v[24:25], v[8:9], v[46:47], v[24:25]
	v_add_f32_e32 v24, v24, v25
	v_pk_fma_f32 v[16:17], v[76:77], v[156:157], v[10:11] op_sel_hi:[1,0,1]
	v_pk_fma_f32 v[18:19], v[78:79], v[156:157], v[8:9] op_sel_hi:[1,0,1]
	v_add_f32_dpp v15, v24, v24 row_ror:8 row_mask:0xf bank_mask:0xf bound_ctrl:1
	ds_read_b128 v[124:127], v48 offset:27648
	ds_read_b128 v[128:131], v48 offset:27904
	v_add_f32_dpp v15, v15, v15 row_ror:4 row_mask:0xf bank_mask:0xf bound_ctrl:1
	ds_read_b128 v[132:135], v48 offset:28160
	ds_read_b128 v[136:139], v48 offset:28416
	v_add_f32_dpp v15, v15, v15 row_ror:2 row_mask:0xf bank_mask:0xf bound_ctrl:1
	s_nop 1
	v_add_f32_dpp v30, v15, v15 row_ror:1 row_mask:0xf bank_mask:0xf bound_ctrl:1
	ds_read_b128 v[56:59], v52
	s_waitcnt lgkmcnt(5)
	v_pk_fma_f32 v[10:11], v[80:81], v[30:31], v[16:17] op_sel_hi:[1,0,1] neg_lo:[0,1,0] neg_hi:[0,1,0]
	v_pk_fma_f32 v[8:9], v[82:83], v[30:31], v[18:19] op_sel_hi:[1,0,1] neg_lo:[0,1,0] neg_hi:[0,1,0]
	v_pk_mul_f32 v[24:25], v[10:11], v[84:85] op_sel:[0,0] op_sel_hi:[0,1]
	v_pk_fma_f32 v[24:25], v[10:11], v[86:87], v[24:25] op_sel:[1,0,0] op_sel_hi:[1,1,1]
	v_pk_fma_f32 v[24:25], v[8:9], v[88:89], v[24:25] op_sel:[0,0,0] op_sel_hi:[0,1,1]
	v_pk_fma_f32 v[24:25], v[8:9], v[90:91], v[24:25] op_sel:[1,0,0] op_sel_hi:[1,1,1]
	v_pk_fma_f32 v[16:17], v[92:93], v[156:157], v[10:11] op_sel:[0,1,0] op_sel_hi:[1,1,1]
	v_pk_fma_f32 v[18:19], v[94:95], v[156:157], v[8:9] op_sel:[0,1,0] op_sel_hi:[1,1,1]
	v_add_f32_dpp v15, v24, v24 row_ror:8 row_mask:0xf bank_mask:0xf bound_ctrl:1
	v_add_f32_dpp v32, v25, v25 row_ror:8 row_mask:0xf bank_mask:0xf bound_ctrl:1
	ds_read_b128 v[76:79], v48 offset:28672
	v_add_f32_dpp v15, v15, v15 row_ror:4 row_mask:0xf bank_mask:0xf bound_ctrl:1
	ds_read_b128 v[80:83], v48 offset:28928
	ds_read_b128 v[84:87], v48 offset:29184
	v_add_f32_dpp v15, v15, v15 row_ror:2 row_mask:0xf bank_mask:0xf bound_ctrl:1
	ds_read_b128 v[88:91], v48 offset:29440
	ds_read_b128 v[160:163], v49 offset:112
	v_add_f32_dpp v30, v15, v15 row_ror:1 row_mask:0xf bank_mask:0xf bound_ctrl:1
	s_waitcnt lgkmcnt(5)
	v_min_u32_e32 v56, v56, v57
	v_min3_u32 v56, v56, v58, v59
	v_pk_fma_f32 v[10:11], v[96:97], v[30:31], v[16:17] op_sel_hi:[1,0,1] neg_lo:[0,1,0] neg_hi:[0,1,0]
	v_pk_fma_f32 v[8:9], v[98:99], v[30:31], v[18:19] op_sel_hi:[1,0,1] neg_lo:[0,1,0] neg_hi:[0,1,0]
	v_pk_mul_f32 v[24:25], v[10:11], v[100:101] op_sel:[0,0] op_sel_hi:[0,1]
	v_pk_fma_f32 v[24:25], v[10:11], v[102:103], v[24:25] op_sel:[1,0,0] op_sel_hi:[1,1,1]
	v_pk_fma_f32 v[24:25], v[8:9], v[104:105], v[24:25] op_sel:[0,0,0] op_sel_hi:[0,1,1]
	v_pk_fma_f32 v[24:25], v[8:9], v[106:107], v[24:25] op_sel:[1,0,0] op_sel_hi:[1,1,1]
	v_pk_fma_f32 v[16:17], v[108:109], v[158:159], v[10:11] op_sel_hi:[1,0,1]
	v_pk_fma_f32 v[18:19], v[110:111], v[158:159], v[8:9] op_sel_hi:[1,0,1]
	v_add_f32_dpp v15, v24, v24 row_ror:8 row_mask:0xf bank_mask:0xf bound_ctrl:1
	v_add_f32_dpp v33, v25, v25 row_ror:8 row_mask:0xf bank_mask:0xf bound_ctrl:1
	ds_read_b128 v[92:95], v48 offset:29696
	v_add_f32_dpp v15, v15, v15 row_ror:4 row_mask:0xf bank_mask:0xf bound_ctrl:1
	ds_read_b128 v[96:99], v48 offset:29952
	ds_read_b128 v[100:103], v48 offset:30208
	v_add_f32_dpp v15, v15, v15 row_ror:2 row_mask:0xf bank_mask:0xf bound_ctrl:1
	ds_read_b128 v[104:107], v48 offset:30464
	s_nop 0
	v_add_f32_dpp v30, v15, v15 row_ror:1 row_mask:0xf bank_mask:0xf bound_ctrl:1
	ds_write2st64_b32 v50, v32, v33 offset0:48 offset1:50
	s_waitcnt lgkmcnt(5)
	v_pk_fma_f32 v[10:11], v[112:113], v[30:31], v[16:17] op_sel_hi:[1,0,1] neg_lo:[0,1,0] neg_hi:[0,1,0]
	v_pk_fma_f32 v[8:9], v[114:115], v[30:31], v[18:19] op_sel_hi:[1,0,1] neg_lo:[0,1,0] neg_hi:[0,1,0]
	v_pk_mul_f32 v[24:25], v[10:11], v[116:117] op_sel:[0,0] op_sel_hi:[0,1]
	v_pk_fma_f32 v[24:25], v[10:11], v[118:119], v[24:25] op_sel:[1,0,0] op_sel_hi:[1,1,1]
	v_pk_fma_f32 v[24:25], v[8:9], v[120:121], v[24:25] op_sel:[0,0,0] op_sel_hi:[0,1,1]
	v_pk_fma_f32 v[24:25], v[8:9], v[122:123], v[24:25] op_sel:[1,0,0] op_sel_hi:[1,1,1]
	v_pk_fma_f32 v[16:17], v[124:125], v[158:159], v[10:11] op_sel:[0,1,0] op_sel_hi:[1,1,1]
	v_pk_fma_f32 v[18:19], v[126:127], v[158:159], v[8:9] op_sel:[0,1,0] op_sel_hi:[1,1,1]
	v_add_f32_dpp v15, v24, v24 row_ror:8 row_mask:0xf bank_mask:0xf bound_ctrl:1
	v_add_f32_dpp v32, v25, v25 row_ror:8 row_mask:0xf bank_mask:0xf bound_ctrl:1
	ds_read_b128 v[108:111], v48 offset:30720
	v_add_f32_dpp v15, v15, v15 row_ror:4 row_mask:0xf bank_mask:0xf bound_ctrl:1
	ds_read_b128 v[112:115], v48 offset:30976
	ds_read_b128 v[116:119], v48 offset:31232
	v_add_f32_dpp v15, v15, v15 row_ror:2 row_mask:0xf bank_mask:0xf bound_ctrl:1
	ds_read_b128 v[120:123], v48 offset:31488
	ds_read_b128 v[40:43], v48 offset:34560
	v_add_f32_dpp v30, v15, v15 row_ror:1 row_mask:0xf bank_mask:0xf bound_ctrl:1
	v_pk_fma_f32 v[10:11], v[128:129], v[30:31], v[16:17] op_sel_hi:[1,0,1] neg_lo:[0,1,0] neg_hi:[0,1,0]
	v_pk_fma_f32 v[8:9], v[130:131], v[30:31], v[18:19] op_sel_hi:[1,0,1] neg_lo:[0,1,0] neg_hi:[0,1,0]
	v_pk_mul_f32 v[24:25], v[10:11], v[132:133] op_sel:[0,0] op_sel_hi:[0,1]
	v_pk_fma_f32 v[24:25], v[10:11], v[134:135], v[24:25] op_sel:[1,0,0] op_sel_hi:[1,1,1]
	v_pk_fma_f32 v[24:25], v[8:9], v[136:137], v[24:25] op_sel:[0,0,0] op_sel_hi:[0,1,1]
	v_pk_fma_f32 v[24:25], v[8:9], v[138:139], v[24:25] op_sel:[1,0,0] op_sel_hi:[1,1,1]
	v_pk_fma_f32 v[16:17], v[76:77], v[160:161], v[10:11] op_sel_hi:[1,0,1]
	v_pk_fma_f32 v[18:19], v[78:79], v[160:161], v[8:9] op_sel_hi:[1,0,1]
	v_add_f32_dpp v15, v24, v24 row_ror:8 row_mask:0xf bank_mask:0xf bound_ctrl:1
	v_add_f32_dpp v33, v25, v25 row_ror:8 row_mask:0xf bank_mask:0xf bound_ctrl:1
	ds_read_b128 v[124:127], v48 offset:31744
	v_add_f32_dpp v15, v15, v15 row_ror:4 row_mask:0xf bank_mask:0xf bound_ctrl:1
	ds_read_b128 v[128:131], v48 offset:32000
	ds_read_b128 v[132:135], v48 offset:32256
	v_add_f32_dpp v15, v15, v15 row_ror:2 row_mask:0xf bank_mask:0xf bound_ctrl:1
	ds_read_b128 v[136:139], v48 offset:32512
	s_nop 0
	v_add_f32_dpp v30, v15, v15 row_ror:1 row_mask:0xf bank_mask:0xf bound_ctrl:1
	ds_write2st64_b32 v50, v32, v33 offset0:52 offset1:54
	v_readfirstlane_b32 s54, v56
	s_add_u32 s64, s6, 2
	s_cmp_lt_u32 s54, s64
	s_cbranch_scc1 .Lss_spin_1
.Lss_ok_1:
	s_waitcnt lgkmcnt(5)
	v_pk_fma_f32 v[10:11], v[80:81], v[30:31], v[16:17] op_sel_hi:[1,0,1] neg_lo:[0,1,0] neg_hi:[0,1,0]
	v_pk_fma_f32 v[8:9], v[82:83], v[30:31], v[18:19] op_sel_hi:[1,0,1] neg_lo:[0,1,0] neg_hi:[0,1,0]
	v_pk_mul_f32 v[24:25], v[10:11], v[84:85] op_sel:[0,0] op_sel_hi:[0,1]
	v_pk_fma_f32 v[24:25], v[10:11], v[86:87], v[24:25] op_sel:[1,0,0] op_sel_hi:[1,1,1]
	v_pk_fma_f32 v[24:25], v[8:9], v[88:89], v[24:25] op_sel:[0,0,0] op_sel_hi:[0,1,1]
	v_pk_fma_f32 v[24:25], v[8:9], v[90:91], v[24:25] op_sel:[1,0,0] op_sel_hi:[1,1,1]
	v_pk_fma_f32 v[16:17], v[92:93], v[160:161], v[10:11] op_sel:[0,1,0] op_sel_hi:[1,1,1]
	v_pk_fma_f32 v[18:19], v[94:95], v[160:161], v[8:9] op_sel:[0,1,0] op_sel_hi:[1,1,1]
	v_add_f32_dpp v15, v24, v24 row_ror:8 row_mask:0xf bank_mask:0xf bound_ctrl:1
	v_add_f32_dpp v32, v25, v25 row_ror:8 row_mask:0xf bank_mask:0xf bound_ctrl:1
	ds_read_b128 v[76:79], v34 offset:0
	v_add_f32_dpp v15, v15, v15 row_ror:4 row_mask:0xf bank_mask:0xf bound_ctrl:1
	ds_read_b128 v[80:83], v34 offset:256
	ds_read_b128 v[84:87], v34 offset:512
	v_add_f32_dpp v15, v15, v15 row_ror:2 row_mask:0xf bank_mask:0xf bound_ctrl:1
	ds_read_b128 v[88:91], v34 offset:768
	ds_read_b128 v[44:47], v34 offset:32768
	v_add_f32_dpp v30, v15, v15 row_ror:1 row_mask:0xf bank_mask:0xf bound_ctrl:1
	v_pk_fma_f32 v[10:11], v[96:97], v[30:31], v[16:17] op_sel_hi:[1,0,1] neg_lo:[0,1,0] neg_hi:[0,1,0]
	v_pk_fma_f32 v[8:9], v[98:99], v[30:31], v[18:19] op_sel_hi:[1,0,1] neg_lo:[0,1,0] neg_hi:[0,1,0]
	v_pk_mul_f32 v[24:25], v[10:11], v[100:101] op_sel:[0,0] op_sel_hi:[0,1]
	v_pk_fma_f32 v[24:25], v[10:11], v[102:103], v[24:25] op_sel:[1,0,0] op_sel_hi:[1,1,1]
	v_pk_fma_f32 v[24:25], v[8:9], v[104:105], v[24:25] op_sel:[0,0,0] op_sel_hi:[0,1,1]
	v_pk_fma_f32 v[24:25], v[8:9], v[106:107], v[24:25] op_sel:[1,0,0] op_sel_hi:[1,1,1]
	v_pk_fma_f32 v[16:17], v[108:109], v[162:163], v[10:11] op_sel_hi:[1,0,1]
	v_pk_fma_f32 v[18:19], v[110:111], v[162:163], v[8:9] op_sel_hi:[1,0,1]
	v_add_f32_dpp v15, v24, v24 row_ror:8 row_mask:0xf bank_mask:0xf bound_ctrl:1
	v_add_f32_dpp v33, v25, v25 row_ror:8 row_mask:0xf bank_mask:0xf bound_ctrl:1
	ds_read_b128 v[92:95], v34 offset:1024
	v_add_f32_dpp v15, v15, v15 row_ror:4 row_mask:0xf bank_mask:0xf bound_ctrl:1
	ds_read_b128 v[96:99], v34 offset:1280
	ds_read_b128 v[100:103], v34 offset:1536
	v_add_f32_dpp v15, v15, v15 row_ror:2 row_mask:0xf bank_mask:0xf bound_ctrl:1
	ds_read_b128 v[104:107], v34 offset:1792
	s_nop 0
	v_add_f32_dpp v30, v15, v15 row_ror:1 row_mask:0xf bank_mask:0xf bound_ctrl:1
	ds_write2st64_b32 v50, v32, v33 offset0:56 offset1:58
	ds_read_b128 v[156:159], v35 offset:0
	s_waitcnt lgkmcnt(6)
	v_pk_fma_f32 v[10:11], v[112:113], v[30:31], v[16:17] op_sel_hi:[1,0,1] neg_lo:[0,1,0] neg_hi:[0,1,0]
	v_pk_fma_f32 v[8:9], v[114:115], v[30:31], v[18:19] op_sel_hi:[1,0,1] neg_lo:[0,1,0] neg_hi:[0,1,0]
	v_pk_mul_f32 v[24:25], v[10:11], v[116:117] op_sel:[0,0] op_sel_hi:[0,1]
	v_pk_fma_f32 v[24:25], v[10:11], v[118:119], v[24:25] op_sel:[1,0,0] op_sel_hi:[1,1,1]
	v_pk_fma_f32 v[24:25], v[8:9], v[120:121], v[24:25] op_sel:[0,0,0] op_sel_hi:[0,1,1]
	v_pk_fma_f32 v[24:25], v[8:9], v[122:123], v[24:25] op_sel:[1,0,0] op_sel_hi:[1,1,1]
	v_pk_fma_f32 v[16:17], v[124:125], v[162:163], v[10:11] op_sel:[0,1,0] op_sel_hi:[1,1,1]
	v_pk_fma_f32 v[18:19], v[126:127], v[162:163], v[8:9] op_sel:[0,1,0] op_sel_hi:[1,1,1]
	v_add_f32_dpp v15, v24, v24 row_ror:8 row_mask:0xf bank_mask:0xf bound_ctrl:1
	v_add_f32_dpp v32, v25, v25 row_ror:8 row_mask:0xf bank_mask:0xf bound_ctrl:1
	ds_read_b128 v[108:111], v34 offset:2048
	v_add_f32_dpp v15, v15, v15 row_ror:4 row_mask:0xf bank_mask:0xf bound_ctrl:1
	ds_read_b128 v[112:115], v34 offset:2304
	ds_read_b128 v[116:119], v34 offset:2560
	v_add_f32_dpp v15, v15, v15 row_ror:2 row_mask:0xf bank_mask:0xf bound_ctrl:1
	ds_read_b128 v[120:123], v34 offset:2816
	s_nop 0
	v_add_f32_dpp v30, v15, v15 row_ror:1 row_mask:0xf bank_mask:0xf bound_ctrl:1
	v_pk_fma_f32 v[10:11], v[128:129], v[30:31], v[16:17] op_sel_hi:[1,0,1] neg_lo:[0,1,0] neg_hi:[0,1,0]
	v_pk_fma_f32 v[8:9], v[130:131], v[30:31], v[18:19] op_sel_hi:[1,0,1] neg_lo:[0,1,0] neg_hi:[0,1,0]
	v_pk_mul_f32 v[24:25], v[10:11], v[132:133] op_sel:[0,0] op_sel_hi:[0,1]
	v_pk_fma_f32 v[24:25], v[10:11], v[134:135], v[24:25] op_sel:[1,0,0] op_sel_hi:[1,1,1]
	v_pk_fma_f32 v[24:25], v[8:9], v[136:137], v[24:25] op_sel:[0,0,0] op_sel_hi:[0,1,1]
	v_pk_fma_f32 v[24:25], v[8:9], v[138:139], v[24:25] op_sel:[1,0,0] op_sel_hi:[1,1,1]
	s_nop 1
	v_add_f32_dpp v33, v25, v25 row_ror:8 row_mask:0xf bank_mask:0xf bound_ctrl:1
	ds_write2st64_b32 v50, v32, v33 offset0:60 offset1:62
	v_pk_mul_f32 v[10:11], v[10:11], v[40:41]
	v_pk_mul_f32 v[8:9], v[8:9], v[42:43]
	v_pk_mul_f32 v[24:25], v[10:11], v[44:45]
	v_pk_fma_f32 v[24:25], v[8:9], v[46:47], v[24:25]
	v_add_f32_e32 v24, v24, v25
	s_waitcnt lgkmcnt(5)
	v_pk_fma_f32 v[16:17], v[76:77], v[156:157], v[10:11] op_sel_hi:[1,0,1]
	v_pk_fma_f32 v[18:19], v[78:79], v[156:157], v[8:9] op_sel_hi:[1,0,1]
	v_add_f32_dpp v15, v24, v24 row_ror:8 row_mask:0xf bank_mask:0xf bound_ctrl:1
	v_add_u32_e32 v51, 1, v51
	s_add_u32 s6, s6, 1
	v_add_f32_dpp v15, v15, v15 row_ror:4 row_mask:0xf bank_mask:0xf bound_ctrl:1
	ds_write_b32 v53, v51
	ds_read_b128 v[124:127], v34 offset:3072
	v_add_f32_dpp v15, v15, v15 row_ror:2 row_mask:0xf bank_mask:0xf bound_ctrl:1
	ds_read_b128 v[128:131], v34 offset:3328
	ds_read_b128 v[132:135], v34 offset:3584
	v_add_f32_dpp v30, v15, v15 row_ror:1 row_mask:0xf bank_mask:0xf bound_ctrl:1
	ds_read_b128 v[136:139], v34 offset:3840
	s_cmp_lt_u32 s6, 0x100
	s_cbranch_scc1 .Lsc_S_loop
	s_waitcnt lgkmcnt(0)
	s_branch .Lsc_item_end
	s_nop 0
	s_nop 0
	s_nop 0
	s_nop 0
	s_nop 0
	s_nop 0
	s_nop 0
	s_nop 0
	s_nop 0
	s_nop 0
	s_nop 0
	s_nop 0
	s_nop 0
	s_nop 0
	s_nop 0
	s_nop 0
	s_nop 0
